# same bookkeeping move in the three 8-phase K-loops that keep their original barriers (pool-mix, w_out, half-merged)
# speedup vs baseline: 1.0141x; 1.0005x over previous
.LBB0_600:
	ds_read_b128 v[128:131], v188
	ds_read_b128 v[132:135], v188 offset:1024
	ds_read_b128 v[136:139], v188 offset:2048
	ds_read_b128 v[140:143], v188 offset:3072
	s_add_u32 s30, s6, 0xfff80080
	s_addc_u32 s31, s7, -1
	s_cmp_eq_u32 s51, 4
	s_cselect_b32 s35, s25, s31
	s_cselect_b32 s34, s24, s30
	s_cselect_b32 s31, s2, s15
	s_cselect_b32 s30, s3, s13
	v_lshl_add_u64 v[202:203], s[6:7], 0, v[160:161]
	s_add_i32 m0, s29, 0xc000
	ds_read_b128 v[144:147], v189
	ds_read_b128 v[148:151], v189 offset:1024
	ds_read_b128 v[168:171], v189 offset:2048
	ds_read_b128 v[172:175], v189 offset:3072
	ds_read_b128 v[176:179], v189 offset:4096
	ds_read_b128 v[180:183], v189 offset:5120
	ds_read_b128 v[194:197], v189 offset:6144
	ds_read_b128 v[198:201], v189 offset:7168
	global_load_lds_dwordx4 v[202:203], off
	v_lshl_add_u64 v[202:203], s[6:7], 0, v[162:163]
	s_add_i32 m0, s29, 0xe000
	s_nop 0
	global_load_lds_dwordx4 v[202:203], off
	s_waitcnt lgkmcnt(8)
	s_barrier
	s_waitcnt lgkmcnt(0)
	s_setprio 1
	s_waitcnt lgkmcnt(0)
	v_mfma_f32_16x16x32_bf16 v[124:127], v[128:131], v[144:147], v[124:127]
	v_mfma_f32_16x16x32_bf16 v[120:123], v[136:139], v[144:147], v[120:123]
	v_mfma_f32_16x16x32_bf16 v[116:119], v[128:131], v[168:171], v[116:119]
	v_mfma_f32_16x16x32_bf16 v[112:115], v[136:139], v[168:171], v[112:115]
	v_mfma_f32_16x16x32_bf16 v[108:111], v[128:131], v[176:179], v[108:111]
	v_mfma_f32_16x16x32_bf16 v[104:107], v[136:139], v[176:179], v[104:107]
	v_mfma_f32_16x16x32_bf16 v[100:103], v[128:131], v[194:197], v[100:103]
	v_mfma_f32_16x16x32_bf16 v[96:99], v[136:139], v[194:197], v[96:99]
	v_mfma_f32_16x16x32_bf16 v[124:127], v[132:135], v[148:151], v[124:127]
	v_mfma_f32_16x16x32_bf16 v[120:123], v[140:143], v[148:151], v[120:123]
	v_mfma_f32_16x16x32_bf16 v[116:119], v[132:135], v[172:175], v[116:119]
	v_mfma_f32_16x16x32_bf16 v[112:115], v[140:143], v[172:175], v[112:115]
	v_mfma_f32_16x16x32_bf16 v[108:111], v[132:135], v[180:183], v[108:111]
	v_mfma_f32_16x16x32_bf16 v[104:107], v[140:143], v[180:183], v[104:107]
	v_mfma_f32_16x16x32_bf16 v[100:103], v[132:135], v[198:201], v[100:103]
	v_mfma_f32_16x16x32_bf16 v[96:99], v[140:143], v[198:201], v[96:99]
	s_setprio 0
	s_barrier
	s_add_i32 s52, s47, s38
	v_lshl_add_u64 v[218:219], s[30:31], 0, v[156:157]
	s_mov_b32 m0, s52
	ds_read_b128 v[202:205], v190
	ds_read_b128 v[206:209], v190 offset:1024
	ds_read_b128 v[210:213], v190 offset:2048
	ds_read_b128 v[214:217], v190 offset:3072
	global_load_lds_dwordx4 v[218:219], off
	v_lshl_add_u64 v[220:221], s[30:31], 0, v[152:153]
	s_add_i32 m0, s52, 0x2000
	s_nop 0
	global_load_lds_dwordx4 v[220:221], off
	s_barrier
	s_waitcnt lgkmcnt(0)
	s_setprio 1
	s_waitcnt lgkmcnt(0)
	v_mfma_f32_16x16x32_bf16 v[60:63], v[202:205], v[144:147], v[60:63]
	v_mfma_f32_16x16x32_bf16 v[56:59], v[210:213], v[144:147], v[56:59]
	v_mfma_f32_16x16x32_bf16 v[52:55], v[202:205], v[168:171], v[52:55]
	v_mfma_f32_16x16x32_bf16 v[48:51], v[210:213], v[168:171], v[48:51]
	v_mfma_f32_16x16x32_bf16 v[44:47], v[202:205], v[176:179], v[44:47]
	v_mfma_f32_16x16x32_bf16 v[40:43], v[210:213], v[176:179], v[40:43]
	v_mfma_f32_16x16x32_bf16 v[36:39], v[202:205], v[194:197], v[36:39]
	v_mfma_f32_16x16x32_bf16 v[32:35], v[210:213], v[194:197], v[32:35]
	v_mfma_f32_16x16x32_bf16 v[60:63], v[206:209], v[148:151], v[60:63]
	v_mfma_f32_16x16x32_bf16 v[56:59], v[214:217], v[148:151], v[56:59]
	v_mfma_f32_16x16x32_bf16 v[52:55], v[206:209], v[172:175], v[52:55]
	v_mfma_f32_16x16x32_bf16 v[48:51], v[214:217], v[172:175], v[48:51]
	v_mfma_f32_16x16x32_bf16 v[44:47], v[206:209], v[180:183], v[44:47]
	v_mfma_f32_16x16x32_bf16 v[40:43], v[214:217], v[180:183], v[40:43]
	v_mfma_f32_16x16x32_bf16 v[36:39], v[206:209], v[198:201], v[36:39]
	v_mfma_f32_16x16x32_bf16 v[32:35], v[214:217], v[198:201], v[32:35]
	s_setprio 0
	s_barrier
	s_mov_b32 m0, s29
	v_lshl_add_u64 v[222:223], s[34:35], 0, v[158:159]
	ds_read_b128 v[144:147], v189 offset:16384
	ds_read_b128 v[148:151], v189 offset:17408
	ds_read_b128 v[168:171], v189 offset:18432
	ds_read_b128 v[172:175], v189 offset:19456
	ds_read_b128 v[176:179], v189 offset:20480
	ds_read_b128 v[180:183], v189 offset:21504
	ds_read_b128 v[194:197], v189 offset:22528
	ds_read_b128 v[198:201], v189 offset:23552
	global_load_lds_dwordx4 v[222:223], off
	v_lshl_add_u64 v[224:225], s[34:35], 0, v[154:155]
	s_mov_b32 m0, s39
	s_nop 0
	global_load_lds_dwordx4 v[224:225], off
	s_barrier
	s_waitcnt lgkmcnt(0)
	s_setprio 1
	s_waitcnt lgkmcnt(0)
	v_mfma_f32_16x16x32_bf16 v[92:95], v[128:131], v[144:147], v[92:95]
	v_mfma_f32_16x16x32_bf16 v[88:91], v[136:139], v[144:147], v[88:91]
	v_mfma_f32_16x16x32_bf16 v[84:87], v[128:131], v[168:171], v[84:87]
	v_mfma_f32_16x16x32_bf16 v[80:83], v[136:139], v[168:171], v[80:83]
	v_mfma_f32_16x16x32_bf16 v[76:79], v[128:131], v[176:179], v[76:79]
	v_mfma_f32_16x16x32_bf16 v[72:75], v[136:139], v[176:179], v[72:75]
	v_mfma_f32_16x16x32_bf16 v[68:71], v[128:131], v[194:197], v[68:71]
	v_mfma_f32_16x16x32_bf16 v[64:67], v[136:139], v[194:197], v[64:67]
	v_mfma_f32_16x16x32_bf16 v[92:95], v[132:135], v[148:151], v[92:95]
	v_mfma_f32_16x16x32_bf16 v[88:91], v[140:143], v[148:151], v[88:91]
	v_mfma_f32_16x16x32_bf16 v[84:87], v[132:135], v[172:175], v[84:87]
	v_mfma_f32_16x16x32_bf16 v[80:83], v[140:143], v[172:175], v[80:83]
	v_mfma_f32_16x16x32_bf16 v[76:79], v[132:135], v[180:183], v[76:79]
	v_mfma_f32_16x16x32_bf16 v[72:75], v[140:143], v[180:183], v[72:75]
	v_mfma_f32_16x16x32_bf16 v[68:71], v[132:135], v[198:201], v[68:71]
	v_mfma_f32_16x16x32_bf16 v[64:67], v[140:143], v[198:201], v[64:67]
	s_setprio 0
	s_barrier
	s_add_u32 s52, s30, 0x20000
	s_addc_u32 s53, s31, 0
	s_add_i32 s54, s48, s38
	v_lshl_add_u64 v[128:129], s[52:53], 0, v[156:157]
	s_mov_b32 m0, s54
	s_nop 0
	global_load_lds_dwordx4 v[128:129], off
	v_lshl_add_u64 v[128:129], s[52:53], 0, v[152:153]
	s_add_i32 m0, s54, 0x2000
	s_nop 0
	global_load_lds_dwordx4 v[128:129], off
	s_waitcnt vmcnt(6)
	s_barrier
	s_setprio 1
	v_mfma_f32_16x16x32_bf16 v[28:31], v[202:205], v[144:147], v[28:31]
	v_mfma_f32_16x16x32_bf16 v[24:27], v[210:213], v[144:147], v[24:27]
	v_mfma_f32_16x16x32_bf16 v[20:23], v[202:205], v[168:171], v[20:23]
	v_mfma_f32_16x16x32_bf16 v[16:19], v[210:213], v[168:171], v[16:19]
	v_mfma_f32_16x16x32_bf16 v[12:15], v[202:205], v[176:179], v[12:15]
	v_mfma_f32_16x16x32_bf16 v[8:11], v[210:213], v[176:179], v[8:11]
	v_mfma_f32_16x16x32_bf16 v[4:7], v[202:205], v[194:197], v[4:7]
	v_mfma_f32_16x16x32_bf16 v[0:3], v[210:213], v[194:197], v[0:3]
	v_mfma_f32_16x16x32_bf16 v[28:31], v[206:209], v[148:151], v[28:31]
	v_mfma_f32_16x16x32_bf16 v[24:27], v[214:217], v[148:151], v[24:27]
	v_mfma_f32_16x16x32_bf16 v[20:23], v[206:209], v[172:175], v[20:23]
	v_mfma_f32_16x16x32_bf16 v[16:19], v[214:217], v[172:175], v[16:19]
	v_mfma_f32_16x16x32_bf16 v[12:15], v[206:209], v[180:183], v[12:15]
	v_mfma_f32_16x16x32_bf16 v[8:11], v[214:217], v[180:183], v[8:11]
	v_mfma_f32_16x16x32_bf16 v[4:7], v[206:209], v[198:201], v[4:7]
	v_mfma_f32_16x16x32_bf16 v[0:3], v[214:217], v[198:201], v[0:3]
	s_setprio 0
	s_barrier
	s_add_i32 s52, 0, 0x18000
	v_add_u32_e32 v140, s52, v186
	ds_read_b128 v[128:131], v140
	ds_read_b128 v[132:135], v140 offset:1024
	ds_read_b128 v[136:139], v140 offset:2048
	ds_read_b128 v[140:143], v140 offset:3072
	s_add_u32 s34, s34, 0x80000
	s_addc_u32 s35, s35, 0
	s_mov_b32 m0, s40
	v_lshl_add_u64 v[202:203], s[34:35], 0, v[158:159]
	ds_read_b128 v[144:147], v189 offset:32768
	ds_read_b128 v[148:151], v189 offset:33792
	ds_read_b128 v[168:171], v189 offset:34816
	ds_read_b128 v[172:175], v189 offset:35840
	ds_read_b128 v[176:179], v189 offset:36864
	ds_read_b128 v[180:183], v189 offset:37888
	ds_read_b128 v[194:197], v189 offset:38912
	ds_read_b128 v[198:201], v189 offset:39936
	global_load_lds_dwordx4 v[202:203], off
	v_lshl_add_u64 v[202:203], s[34:35], 0, v[154:155]
	s_mov_b32 m0, s41
	s_nop 0
	global_load_lds_dwordx4 v[202:203], off
	s_waitcnt lgkmcnt(8)
	s_barrier
	s_waitcnt lgkmcnt(0)
	s_setprio 1
	s_waitcnt lgkmcnt(0)
	v_mfma_f32_16x16x32_bf16 v[124:127], v[128:131], v[144:147], v[124:127]
	v_mfma_f32_16x16x32_bf16 v[120:123], v[136:139], v[144:147], v[120:123]
	v_mfma_f32_16x16x32_bf16 v[116:119], v[128:131], v[168:171], v[116:119]
	v_mfma_f32_16x16x32_bf16 v[112:115], v[136:139], v[168:171], v[112:115]
	v_mfma_f32_16x16x32_bf16 v[108:111], v[128:131], v[176:179], v[108:111]
	v_mfma_f32_16x16x32_bf16 v[104:107], v[136:139], v[176:179], v[104:107]
	v_mfma_f32_16x16x32_bf16 v[100:103], v[128:131], v[194:197], v[100:103]
	v_mfma_f32_16x16x32_bf16 v[96:99], v[136:139], v[194:197], v[96:99]
	v_mfma_f32_16x16x32_bf16 v[124:127], v[132:135], v[148:151], v[124:127]
	v_mfma_f32_16x16x32_bf16 v[120:123], v[140:143], v[148:151], v[120:123]
	v_mfma_f32_16x16x32_bf16 v[116:119], v[132:135], v[172:175], v[116:119]
	v_mfma_f32_16x16x32_bf16 v[112:115], v[140:143], v[172:175], v[112:115]
	v_mfma_f32_16x16x32_bf16 v[108:111], v[132:135], v[180:183], v[108:111]
	v_mfma_f32_16x16x32_bf16 v[104:107], v[140:143], v[180:183], v[104:107]
	v_mfma_f32_16x16x32_bf16 v[100:103], v[132:135], v[198:201], v[100:103]
	v_mfma_f32_16x16x32_bf16 v[96:99], v[140:143], v[198:201], v[96:99]
	s_setprio 0
	s_barrier
	s_add_i32 s34, 0, 0x1c000
	s_add_i32 s35, s52, s38
	v_add_u32_e32 v191, s34, v186
	v_lshl_add_u64 v[218:219], v[218:219], 0, s[0:1]
	s_mov_b32 m0, s35
	ds_read_b128 v[202:205], v191
	ds_read_b128 v[206:209], v191 offset:1024
	ds_read_b128 v[210:213], v191 offset:2048
	ds_read_b128 v[214:217], v191 offset:3072
	global_load_lds_dwordx4 v[218:219], off
	v_lshl_add_u64 v[218:219], v[220:221], 0, s[0:1]
	s_add_i32 m0, s35, 0x2000
	s_nop 0
	global_load_lds_dwordx4 v[218:219], off
	s_barrier
	s_waitcnt lgkmcnt(0)
	s_setprio 1
	s_waitcnt lgkmcnt(0)
	v_mfma_f32_16x16x32_bf16 v[60:63], v[202:205], v[144:147], v[60:63]
	v_mfma_f32_16x16x32_bf16 v[56:59], v[210:213], v[144:147], v[56:59]
	v_mfma_f32_16x16x32_bf16 v[52:55], v[202:205], v[168:171], v[52:55]
	v_mfma_f32_16x16x32_bf16 v[48:51], v[210:213], v[168:171], v[48:51]
	v_mfma_f32_16x16x32_bf16 v[44:47], v[202:205], v[176:179], v[44:47]
	v_mfma_f32_16x16x32_bf16 v[40:43], v[210:213], v[176:179], v[40:43]
	v_mfma_f32_16x16x32_bf16 v[36:39], v[202:205], v[194:197], v[36:39]
	v_mfma_f32_16x16x32_bf16 v[32:35], v[210:213], v[194:197], v[32:35]
	v_mfma_f32_16x16x32_bf16 v[60:63], v[206:209], v[148:151], v[60:63]
	v_mfma_f32_16x16x32_bf16 v[56:59], v[214:217], v[148:151], v[56:59]
	v_mfma_f32_16x16x32_bf16 v[52:55], v[206:209], v[172:175], v[52:55]
	v_mfma_f32_16x16x32_bf16 v[48:51], v[214:217], v[172:175], v[48:51]
	v_mfma_f32_16x16x32_bf16 v[44:47], v[206:209], v[180:183], v[44:47]
	v_mfma_f32_16x16x32_bf16 v[40:43], v[214:217], v[180:183], v[40:43]
	v_mfma_f32_16x16x32_bf16 v[36:39], v[206:209], v[198:201], v[36:39]
	v_mfma_f32_16x16x32_bf16 v[32:35], v[214:217], v[198:201], v[32:35]
	s_setprio 0
	s_barrier
	s_mov_b32 m0, s43
	v_lshl_add_u64 v[218:219], v[222:223], 0, s[0:1]
	ds_read_b128 v[144:147], v189 offset:49152
	ds_read_b128 v[148:151], v189 offset:50176
	ds_read_b128 v[168:171], v189 offset:51200
	ds_read_b128 v[172:175], v189 offset:52224
	ds_read_b128 v[176:179], v189 offset:53248
	ds_read_b128 v[180:183], v189 offset:54272
	ds_read_b128 v[194:197], v189 offset:55296
	ds_read_b128 v[198:201], v189 offset:56320
	global_load_lds_dwordx4 v[218:219], off
	v_lshl_add_u64 v[218:219], v[224:225], 0, s[0:1]
	s_mov_b32 m0, s44
	s_nop 0
	global_load_lds_dwordx4 v[218:219], off
	s_barrier
; __device__ __forceinline__ float bflo(unsigned w) { return __uint_as_float(w << 16); }
; __device__ __forceinline__ float bfhi(unsigned w) { return __uint_as_float(w & 0xffff0000u); }
; __device__ __forceinline__ unsigned pk2(float lo, float hi) { unsigned r; asm("v_cvt_pk_bf16_f32 %0, %1, %2" : "=v"(r) : "v"(lo), "v"(hi)); return r; }
; __device__ __forceinline__ float siluf_(float x) { return x * __builtin_amdgcn_rcpf(1.0f + __expf(-x)); }
;     __device__ __forceinline__ void operator()(const f32x4 (&acc)[2][2][4][2], const Unit& u, int wr, int wc, int fr, int fq) const {
;         const int row0 = u.pm * BM + wr * 64 + fr, col0 = u.pn * BM + wc * 32 + 8 * fq;
; #pragma unroll
;         for (int bj = 0; bj < 2; ++bj) { const int col = col0 + bj * HALF;
;             const f32x4 b0 = *(const f32x4*)(bias + col), b1 = *(const f32x4*)(bias + col + 4), s0 = *(const f32x4*)(scale + col), s1 = *(const f32x4*)(scale + col + 4);
; #pragma unroll
;             for (int ai = 0; ai < 2; ++ai)
; #pragma unroll
;                 for (int m = 0; m < 4; ++m) { const int row = row0 + ai * HALF + m * 16;
;                     const u32x4 z = __builtin_nontemporal_load((const u32x4*)(proj + (size_t)row * NPROJ + C_ZP + col));
;                     f32x4 v0 = (acc[ai][bj][m][0] + b0) * s0, v1 = (acc[ai][bj][m][1] + b1) * s1;
;                     v0[0] *= siluf_(bflo(z.x)); v0[1] *= siluf_(bfhi(z.x)); v0[2] *= siluf_(bflo(z.y)); v0[3] *= siluf_(bfhi(z.y));
;                     v1[0] *= siluf_(bflo(z.z)); v1[1] *= siluf_(bfhi(z.z)); v1[2] *= siluf_(bflo(z.w)); v1[3] *= siluf_(bfhi(z.w));
;                     u32x4 w; w.x = pk2(v0[0], v0[1]); w.y = pk2(v0[2], v0[3]); w.z = pk2(v1[0], v1[1]); w.w = pk2(v1[2], v1[3]);
;                     *(u32x4*)(a2 + (size_t)row * 4096 + 2048 + col) = w; } }
	s_waitcnt lgkmcnt(0)
	s_setprio 1
	s_waitcnt lgkmcnt(0)
	v_mfma_f32_16x16x32_bf16 v[92:95], v[128:131], v[144:147], v[92:95]
	v_mfma_f32_16x16x32_bf16 v[88:91], v[136:139], v[144:147], v[88:91]
	v_mfma_f32_16x16x32_bf16 v[84:87], v[128:131], v[168:171], v[84:87]
	v_mfma_f32_16x16x32_bf16 v[80:83], v[136:139], v[168:171], v[80:83]
	v_mfma_f32_16x16x32_bf16 v[76:79], v[128:131], v[176:179], v[76:79]
	v_mfma_f32_16x16x32_bf16 v[72:75], v[136:139], v[176:179], v[72:75]
	v_mfma_f32_16x16x32_bf16 v[68:71], v[128:131], v[194:197], v[68:71]
	v_mfma_f32_16x16x32_bf16 v[64:67], v[136:139], v[194:197], v[64:67]
	v_mfma_f32_16x16x32_bf16 v[92:95], v[132:135], v[148:151], v[92:95]
	v_mfma_f32_16x16x32_bf16 v[88:91], v[140:143], v[148:151], v[88:91]
	v_mfma_f32_16x16x32_bf16 v[84:87], v[132:135], v[172:175], v[84:87]
	v_mfma_f32_16x16x32_bf16 v[80:83], v[140:143], v[172:175], v[80:83]
	v_mfma_f32_16x16x32_bf16 v[76:79], v[132:135], v[180:183], v[76:79]
	v_mfma_f32_16x16x32_bf16 v[72:75], v[140:143], v[180:183], v[72:75]
	v_mfma_f32_16x16x32_bf16 v[68:71], v[132:135], v[198:201], v[68:71]
	v_mfma_f32_16x16x32_bf16 v[64:67], v[140:143], v[198:201], v[64:67]
	s_setprio 0
	s_barrier
	s_add_u32 s30, s30, 0x20080
	s_addc_u32 s31, s31, 0
	s_add_i32 s34, s34, s38
	v_lshl_add_u64 v[128:129], s[30:31], 0, v[156:157]
	s_mov_b32 m0, s34
	s_nop 0
	global_load_lds_dwordx4 v[128:129], off
	v_lshl_add_u64 v[128:129], s[30:31], 0, v[152:153]
	s_add_i32 m0, s34, 0x2000
	s_nop 0
	global_load_lds_dwordx4 v[128:129], off
	s_add_i32 s51, s51, 2
	s_add_u32 s6, s6, 0x100
	s_addc_u32 s7, s7, 0
	s_add_u32 s13, s13, 0x100
	s_addc_u32 s15, s15, 0
	s_cmp_gt_u32 s51, 5
	s_waitcnt vmcnt(6)
	s_barrier
	s_setprio 1
	v_mfma_f32_16x16x32_bf16 v[28:31], v[202:205], v[144:147], v[28:31]
	v_mfma_f32_16x16x32_bf16 v[24:27], v[210:213], v[144:147], v[24:27]
	v_mfma_f32_16x16x32_bf16 v[20:23], v[202:205], v[168:171], v[20:23]
	v_mfma_f32_16x16x32_bf16 v[16:19], v[210:213], v[168:171], v[16:19]
	v_mfma_f32_16x16x32_bf16 v[12:15], v[202:205], v[176:179], v[12:15]
	v_mfma_f32_16x16x32_bf16 v[8:11], v[210:213], v[176:179], v[8:11]
	v_mfma_f32_16x16x32_bf16 v[4:7], v[202:205], v[194:197], v[4:7]
	v_mfma_f32_16x16x32_bf16 v[0:3], v[210:213], v[194:197], v[0:3]
	v_mfma_f32_16x16x32_bf16 v[28:31], v[206:209], v[148:151], v[28:31]
	v_mfma_f32_16x16x32_bf16 v[24:27], v[214:217], v[148:151], v[24:27]
	v_mfma_f32_16x16x32_bf16 v[20:23], v[206:209], v[172:175], v[20:23]
	v_mfma_f32_16x16x32_bf16 v[16:19], v[214:217], v[172:175], v[16:19]
	v_mfma_f32_16x16x32_bf16 v[12:15], v[206:209], v[180:183], v[12:15]
	v_mfma_f32_16x16x32_bf16 v[8:11], v[214:217], v[180:183], v[8:11]
	v_mfma_f32_16x16x32_bf16 v[4:7], v[206:209], v[198:201], v[4:7]
	v_mfma_f32_16x16x32_bf16 v[0:3], v[214:217], v[198:201], v[0:3]
	s_setprio 0
	s_barrier
	s_cbranch_scc0 .LBB0_600
	v_lshl_add_u32 v176, s28, 8, v185
	v_lshl_or_b32 v148, s50, 8, v187
	v_mov_b64_e32 v[178:179], s[92:93]
	v_ashrrev_i32_e32 v149, 31, v148
	v_readlane_b32 s52, v244, 0
	v_mad_i64_i32 v[138:139], s[2:3], v176, s49, v[178:179]
	v_lshlrev_b64 v[136:137], 2, v[148:149]
	v_readlane_b32 s53, v244, 1
	v_lshl_add_u64 v[150:151], v[138:139], 0, s[8:9]
	v_lshlrev_b64 v[174:175], 1, v[148:149]
	v_lshl_add_u64 v[170:171], s[52:53], 0, v[136:137]
	v_lshl_add_u64 v[138:139], v[150:151], 0, v[174:175]
	global_load_dwordx4 v[128:131], v[170:171], off offset:16
	global_load_dwordx4 v[132:135], v[170:171], off
	v_mov_b32_e32 v254, v138
	v_mov_b32_e32 v255, v139
	global_load_dwordx4 v[144:147], v[138:139], off nt
	v_readlane_b32 s54, v244, 2
	v_readlane_b32 s55, v244, 3
	v_ashrrev_i32_e32 v177, 31, v176
	v_lshlrev_b64 v[168:169], 13, v[176:177]
	v_lshl_add_u64 v[172:173], s[54:55], 0, v[136:137]
	global_load_dwordx4 v[140:143], v[172:173], off
	global_load_dwordx4 v[136:139], v[172:173], off offset:16
	v_readlane_b32 s6, v244, 45
	v_readlane_b32 s7, v244, 46
	v_or_b32_e32 v182, 16, v176
	v_mad_i64_i32 v[194:195], s[2:3], v182, s49, v[178:179]
	v_lshl_add_u64 v[180:181], s[6:7], 0, v[168:169]
	v_lshl_add_u64 v[180:181], v[180:181], 0, s[10:11]
	v_lshl_add_u64 v[196:197], v[180:181], 0, v[174:175]
	v_or_b32_e32 v148, 0x80, v148
	v_ashrrev_i32_e32 v149, 31, v148
	v_lshlrev_b64 v[168:169], 1, v[148:149]
	v_lshl_add_u64 v[148:149], v[150:151], 0, v[168:169]
	global_load_dwordx4 v[148:151], v[148:149], off nt
	global_load_dwordx4 v[234:237], v[170:171], off offset:512
	global_load_dwordx4 v[238:241], v[170:171], off offset:528
	global_load_dwordx4 v[246:249], v[172:173], off offset:512
	global_load_dwordx4 v[250:253], v[172:173], off offset:528
	s_mov_b32 s60, 0x6a000
	s_mov_b32 s61, 0
	v_lshl_add_u64 v[206:207], v[254:255], 0, s[60:61]
	global_load_dwordx4 v[206:209], v[206:207], off nt
	s_mov_b32 s60, 0xd4000
	s_mov_b32 s61, 0
	v_lshl_add_u64 v[210:211], v[254:255], 0, s[60:61]
	global_load_dwordx4 v[210:213], v[210:211], off nt
	s_mov_b32 s60, 0x13e000
	s_mov_b32 s61, 0
	v_lshl_add_u64 v[214:215], v[254:255], 0, s[60:61]
	global_load_dwordx4 v[214:217], v[214:215], off nt
	s_mov_b32 s60, 0x350000
	s_mov_b32 s61, 0
	v_lshl_add_u64 v[218:219], v[254:255], 0, s[60:61]
	global_load_dwordx4 v[218:221], v[218:219], off nt
	s_mov_b32 s60, 0x3ba000
	s_mov_b32 s61, 0
	v_lshl_add_u64 v[222:223], v[254:255], 0, s[60:61]
	global_load_dwordx4 v[222:225], v[222:223], off nt
	s_mov_b32 s60, 0x424000
	s_mov_b32 s61, 0
	v_lshl_add_u64 v[226:227], v[254:255], 0, s[60:61]
	global_load_dwordx4 v[226:229], v[226:227], off nt
	s_mov_b32 s60, 0x48e000
	s_mov_b32 s61, 0
	v_lshl_add_u64 v[230:231], v[254:255], 0, s[60:61]
	global_load_dwordx4 v[230:233], v[230:231], off nt
	s_and_b64 vcc, exec, s[4:5]
	s_mov_b32 s50, s12
	s_mov_b32 s28, s14
	s_mov_b64 s[30:31], s[26:27]
	s_mov_b64 s[34:35], s[24:25]
	v_readlane_b32 s56, v244, 4
	v_readlane_b32 s57, v244, 5
	v_readlane_b32 s58, v244, 6
	v_readlane_b32 s59, v244, 7
	s_waitcnt vmcnt(12)
; __device__ __forceinline__ float bflo(unsigned w) { return __uint_as_float(w << 16); }
; __device__ __forceinline__ float bfhi(unsigned w) { return __uint_as_float(w & 0xffff0000u); }
; __device__ __forceinline__ unsigned pk2(float lo, float hi) { unsigned r; asm("v_cvt_pk_bf16_f32 %0, %1, %2" : "=v"(r) : "v"(lo), "v"(hi)); return r; }
; __device__ __forceinline__ float siluf_(float x) { return x * __builtin_amdgcn_rcpf(1.0f + __expf(-x)); }
;     __device__ __forceinline__ void operator()(const f32x4 (&acc)[2][2][4][2], const Unit& u, int wr, int wc, int fr, int fq) const {
;         const int row0 = u.pm * BM + wr * 64 + fr, col0 = u.pn * BM + wc * 32 + 8 * fq;
; #pragma unroll
;         for (int bj = 0; bj < 2; ++bj) { const int col = col0 + bj * HALF;
;             const f32x4 b0 = *(const f32x4*)(bias + col), b1 = *(const f32x4*)(bias + col + 4), s0 = *(const f32x4*)(scale + col), s1 = *(const f32x4*)(scale + col + 4);
; #pragma unroll
;             for (int ai = 0; ai < 2; ++ai)
; #pragma unroll
;                 for (int m = 0; m < 4; ++m) { const int row = row0 + ai * HALF + m * 16;
;                     const u32x4 z = __builtin_nontemporal_load((const u32x4*)(proj + (size_t)row * NPROJ + C_ZP + col));
;                     f32x4 v0 = (acc[ai][bj][m][0] + b0) * s0, v1 = (acc[ai][bj][m][1] + b1) * s1;
;                     v0[0] *= siluf_(bflo(z.x)); v0[1] *= siluf_(bfhi(z.x)); v0[2] *= siluf_(bflo(z.y)); v0[3] *= siluf_(bfhi(z.y));
;                     v1[0] *= siluf_(bflo(z.z)); v1[1] *= siluf_(bfhi(z.z)); v1[2] *= siluf_(bflo(z.w)); v1[3] *= siluf_(bfhi(z.w));
;                     u32x4 w; w.x = pk2(v0[0], v0[1]); w.y = pk2(v0[2], v0[3]); w.z = pk2(v1[0], v1[1]); w.w = pk2(v1[2], v1[3]);
;                     *(u32x4*)(a2 + (size_t)row * 4096 + 2048 + col) = w; } }
	v_pk_add_f32 v[122:123], v[122:123], v[130:131]
	v_pk_add_f32 v[124:125], v[124:125], v[132:133]
	v_lshlrev_b32_e32 v177, 16, v144
	v_and_b32_e32 v144, 0xffff0000, v144
	v_lshlrev_b32_e32 v183, 16, v145
	v_and_b32_e32 v145, 0xffff0000, v145
	v_lshlrev_b32_e32 v191, 16, v146
	v_and_b32_e32 v146, 0xffff0000, v146
	v_lshlrev_b32_e32 v193, 16, v147
	v_and_b32_e32 v147, 0xffff0000, v147
	v_mul_f32_e32 v198, 0xbfb8aa3b, v177
	v_mul_f32_e32 v199, 0xbfb8aa3b, v144
	v_mul_f32_e32 v200, 0xbfb8aa3b, v183
	v_mul_f32_e32 v201, 0xbfb8aa3b, v145
	v_mul_f32_e32 v202, 0xbfb8aa3b, v191
	v_mul_f32_e32 v203, 0xbfb8aa3b, v146
	v_mul_f32_e32 v205, 0xbfb8aa3b, v147
	v_exp_f32_e32 v198, v198
	v_exp_f32_e32 v199, v199
	v_mul_f32_e32 v204, 0xbfb8aa3b, v193
	v_exp_f32_e32 v200, v200
	v_exp_f32_e32 v201, v201
	v_exp_f32_e32 v202, v202
	v_exp_f32_e32 v203, v203
	v_exp_f32_e32 v205, v205
	v_exp_f32_e32 v204, v204
	v_add_f32_e32 v198, 1.0, v198
	v_add_f32_e32 v199, 1.0, v199
	v_add_f32_e32 v200, 1.0, v200
	v_add_f32_e32 v201, 1.0, v201
	v_add_f32_e32 v202, 1.0, v202
	v_add_f32_e32 v203, 1.0, v203
	v_add_f32_e32 v205, 1.0, v205
	v_rcp_f32_e32 v198, v198
	v_rcp_f32_e32 v199, v199
	v_add_f32_e32 v204, 1.0, v204
	v_rcp_f32_e32 v200, v200
	v_rcp_f32_e32 v201, v201
	v_rcp_f32_e32 v202, v202
	v_rcp_f32_e32 v203, v203
	v_rcp_f32_e32 v205, v205
	v_rcp_f32_e32 v204, v204
	v_pk_add_f32 v[126:127], v[126:127], v[134:135]
	v_pk_add_f32 v[120:121], v[120:121], v[128:129]
	v_pk_mul_f32 v[124:125], v[124:125], v[140:141]
	v_mul_f32_e32 v177, v198, v177
	v_mul_f32_e32 v144, v199, v144
	v_pk_mul_f32 v[126:127], v[126:127], v[142:143]
	v_pk_mul_f32 v[122:123], v[122:123], v[138:139]
	v_pk_mul_f32 v[120:121], v[120:121], v[136:137]
	v_mul_f32_e32 v183, v200, v183
	v_mul_f32_e32 v145, v201, v145
	v_mul_f32_e32 v191, v202, v191
	v_mul_f32_e32 v146, v203, v146
	v_mul_f32_e32 v147, v205, v147
	v_mul_f32_e32 v124, v124, v177
	v_mul_f32_e32 v125, v125, v144
	v_mul_f32_e32 v193, v204, v193
	v_mul_f32_e32 v126, v126, v183
	v_mul_f32_e32 v127, v127, v145
	v_mul_f32_e32 v144, v120, v191
	v_mul_f32_e32 v145, v121, v146
	v_mul_f32_e32 v123, v123, v147
	v_cvt_pk_bf16_f32 v120, v124, v125
	v_cvt_pk_bf16_f32 v121, v126, v127
	v_lshl_add_u64 v[124:125], v[194:195], 0, s[8:9]
	v_mul_f32_e32 v146, v122, v193
	v_cvt_pk_bf16_f32 v122, v144, v145
	v_cvt_pk_bf16_f32 v123, v146, v123
	global_store_dwordx4 v[196:197], v[120:123], off
	v_ashrrev_i32_e32 v183, 31, v182
	v_or_b32_e32 v126, 32, v176
	v_lshl_add_u64 v[120:121], v[124:125], 0, v[174:175]
	v_lshlrev_b64 v[122:123], 13, v[182:183]
	v_lshl_add_u64 v[122:123], s[6:7], 0, v[122:123]
	v_pk_add_f32 v[114:115], v[114:115], v[130:131]
	v_mad_i64_i32 v[120:121], s[2:3], v126, s49, v[178:179]
	v_lshl_add_u64 v[122:123], v[122:123], 0, s[10:11]
	v_pk_add_f32 v[118:119], v[118:119], v[134:135]
	v_pk_add_f32 v[116:117], v[116:117], v[132:133]
	v_pk_add_f32 v[112:113], v[112:113], v[128:129]
	v_pk_mul_f32 v[114:115], v[114:115], v[138:139]
	v_lshl_add_u64 v[120:121], v[120:121], 0, s[8:9]
	v_lshl_add_u64 v[194:195], v[122:123], 0, v[174:175]
	v_pk_mul_f32 v[118:119], v[118:119], v[142:143]
	v_pk_mul_f32 v[116:117], v[116:117], v[140:141]
	v_pk_mul_f32 v[112:113], v[112:113], v[136:137]
	v_lshl_add_u64 v[182:183], v[120:121], 0, v[174:175]
	v_pk_add_f32 v[106:107], v[106:107], v[130:131]
	v_pk_add_f32 v[110:111], v[110:111], v[134:135]
	v_pk_add_f32 v[108:109], v[108:109], v[132:133]
	v_pk_add_f32 v[104:105], v[104:105], v[128:129]
	v_pk_mul_f32 v[106:107], v[106:107], v[138:139]
	v_pk_mul_f32 v[110:111], v[110:111], v[142:143]
	v_pk_mul_f32 v[108:109], v[108:109], v[140:141]
	v_pk_mul_f32 v[104:105], v[104:105], v[136:137]
	v_pk_add_f32 v[98:99], v[98:99], v[130:131]
	v_pk_add_f32 v[102:103], v[102:103], v[134:135]
	v_pk_add_f32 v[100:101], v[100:101], v[132:133]
	v_pk_add_f32 v[96:97], v[96:97], v[128:129]
	v_pk_mul_f32 v[98:99], v[98:99], v[138:139]
	v_pk_mul_f32 v[102:103], v[102:103], v[142:143]
	v_pk_mul_f32 v[100:101], v[100:101], v[140:141]
	v_pk_mul_f32 v[96:97], v[96:97], v[136:137]
	v_pk_add_f32 v[90:91], v[90:91], v[130:131]
	v_pk_add_f32 v[94:95], v[94:95], v[134:135]
	v_pk_add_f32 v[92:93], v[92:93], v[132:133]
	v_pk_add_f32 v[88:89], v[88:89], v[128:129]
	v_pk_mul_f32 v[90:91], v[90:91], v[138:139]
	v_pk_mul_f32 v[94:95], v[94:95], v[142:143]
	v_pk_mul_f32 v[92:93], v[92:93], v[140:141]
	v_pk_mul_f32 v[88:89], v[88:89], v[136:137]
	v_pk_add_f32 v[82:83], v[82:83], v[130:131]
	v_pk_add_f32 v[86:87], v[86:87], v[134:135]
	v_pk_add_f32 v[84:85], v[84:85], v[132:133]
	v_pk_add_f32 v[80:81], v[80:81], v[128:129]
	v_pk_mul_f32 v[82:83], v[82:83], v[138:139]
	v_pk_mul_f32 v[86:87], v[86:87], v[142:143]
	v_pk_mul_f32 v[84:85], v[84:85], v[140:141]
	v_pk_mul_f32 v[80:81], v[80:81], v[136:137]
	v_pk_add_f32 v[74:75], v[74:75], v[130:131]
	v_pk_add_f32 v[78:79], v[78:79], v[134:135]
	v_pk_add_f32 v[76:77], v[76:77], v[132:133]
	v_pk_add_f32 v[72:73], v[72:73], v[128:129]
	v_pk_mul_f32 v[74:75], v[74:75], v[138:139]
	v_pk_mul_f32 v[78:79], v[78:79], v[142:143]
	v_pk_mul_f32 v[76:77], v[76:77], v[140:141]
	v_pk_mul_f32 v[72:73], v[72:73], v[136:137]
	v_pk_add_f32 v[66:67], v[66:67], v[130:131]
	v_pk_add_f32 v[70:71], v[70:71], v[134:135]
	v_pk_add_f32 v[68:69], v[68:69], v[132:133]
	v_pk_add_f32 v[64:65], v[64:65], v[128:129]
	v_pk_mul_f32 v[66:67], v[66:67], v[138:139]
	v_pk_mul_f32 v[70:71], v[70:71], v[142:143]
	v_pk_mul_f32 v[68:69], v[68:69], v[140:141]
	v_pk_mul_f32 v[64:65], v[64:65], v[136:137]
	s_waitcnt vmcnt(7)
; __device__ __forceinline__ float bflo(unsigned w) { return __uint_as_float(w << 16); }
; __device__ __forceinline__ float bfhi(unsigned w) { return __uint_as_float(w & 0xffff0000u); }
; __device__ __forceinline__ unsigned pk2(float lo, float hi) { unsigned r; asm("v_cvt_pk_bf16_f32 %0, %1, %2" : "=v"(r) : "v"(lo), "v"(hi)); return r; }
; __device__ __forceinline__ float siluf_(float x) { return x * __builtin_amdgcn_rcpf(1.0f + __expf(-x)); }
;     __device__ __forceinline__ void operator()(const f32x4 (&acc)[2][2][4][2], const Unit& u, int wr, int wc, int fr, int fq) const {
;         const int row0 = u.pm * BM + wr * 64 + fr, col0 = u.pn * BM + wc * 32 + 8 * fq;
; #pragma unroll
;         for (int bj = 0; bj < 2; ++bj) { const int col = col0 + bj * HALF;
;             const f32x4 b0 = *(const f32x4*)(bias + col), b1 = *(const f32x4*)(bias + col + 4), s0 = *(const f32x4*)(scale + col), s1 = *(const f32x4*)(scale + col + 4);
; #pragma unroll
;             for (int ai = 0; ai < 2; ++ai)
; #pragma unroll
;                 for (int m = 0; m < 4; ++m) { const int row = row0 + ai * HALF + m * 16;
;                     const u32x4 z = __builtin_nontemporal_load((const u32x4*)(proj + (size_t)row * NPROJ + C_ZP + col));
;                     f32x4 v0 = (acc[ai][bj][m][0] + b0) * s0, v1 = (acc[ai][bj][m][1] + b1) * s1;
;                     v0[0] *= siluf_(bflo(z.x)); v0[1] *= siluf_(bfhi(z.x)); v0[2] *= siluf_(bflo(z.y)); v0[3] *= siluf_(bfhi(z.y));
;                     v1[0] *= siluf_(bflo(z.z)); v1[1] *= siluf_(bfhi(z.z)); v1[2] *= siluf_(bflo(z.w)); v1[3] *= siluf_(bfhi(z.w));
;                     u32x4 w; w.x = pk2(v0[0], v0[1]); w.y = pk2(v0[2], v0[3]); w.z = pk2(v1[0], v1[1]); w.w = pk2(v1[2], v1[3]);
;                     *(u32x4*)(a2 + (size_t)row * 4096 + 2048 + col) = w; } }
	v_mov_b32_e32 v144, v206
	v_mov_b32_e32 v145, v207
	v_mov_b32_e32 v146, v208
	v_mov_b32_e32 v147, v209
	s_mov_b32 s60, 0x6a100
	s_mov_b32 s61, 0
	v_lshl_add_u64 v[206:207], v[254:255], 0, s[60:61]
	global_load_dwordx4 v[206:209], v[206:207], off nt
	v_lshlrev_b32_e32 v193, 16, v147
	v_and_b32_e32 v147, 0xffff0000, v147
	v_lshlrev_b32_e32 v127, 16, v144
	v_and_b32_e32 v144, 0xffff0000, v144
	v_lshlrev_b32_e32 v177, 16, v145
	v_and_b32_e32 v145, 0xffff0000, v145
	v_lshlrev_b32_e32 v191, 16, v146
	v_and_b32_e32 v146, 0xffff0000, v146
	v_mul_f32_e32 v203, 0xbfb8aa3b, v147
	v_mul_f32_e32 v196, 0xbfb8aa3b, v127
	v_mul_f32_e32 v197, 0xbfb8aa3b, v144
	v_mul_f32_e32 v198, 0xbfb8aa3b, v177
	v_mul_f32_e32 v199, 0xbfb8aa3b, v145
	v_mul_f32_e32 v200, 0xbfb8aa3b, v191
	v_mul_f32_e32 v201, 0xbfb8aa3b, v146
	v_mul_f32_e32 v202, 0xbfb8aa3b, v193
	v_exp_f32_e32 v203, v203
	v_exp_f32_e32 v196, v196
	v_exp_f32_e32 v197, v197
	v_exp_f32_e32 v198, v198
	v_exp_f32_e32 v199, v199
	v_exp_f32_e32 v200, v200
	v_exp_f32_e32 v201, v201
	v_exp_f32_e32 v202, v202
	v_add_f32_e32 v203, 1.0, v203
	v_add_f32_e32 v196, 1.0, v196
	v_add_f32_e32 v197, 1.0, v197
	v_add_f32_e32 v198, 1.0, v198
	v_add_f32_e32 v199, 1.0, v199
	v_add_f32_e32 v200, 1.0, v200
	v_add_f32_e32 v201, 1.0, v201
	v_add_f32_e32 v202, 1.0, v202
	v_rcp_f32_e32 v203, v203
	v_rcp_f32_e32 v196, v196
	v_rcp_f32_e32 v197, v197
	v_rcp_f32_e32 v198, v198
	v_rcp_f32_e32 v199, v199
	v_rcp_f32_e32 v200, v200
	v_rcp_f32_e32 v201, v201
	v_rcp_f32_e32 v202, v202
	v_mul_f32_e32 v147, v203, v147
	v_mul_f32_e32 v127, v196, v127
	v_mul_f32_e32 v144, v197, v144
	v_mul_f32_e32 v177, v198, v177
	v_mul_f32_e32 v145, v199, v145
	v_mul_f32_e32 v191, v200, v191
	v_mul_f32_e32 v146, v201, v146
	v_mul_f32_e32 v193, v202, v193
	v_mul_f32_e32 v115, v115, v147
	v_mul_f32_e32 v116, v116, v127
	v_mul_f32_e32 v117, v117, v144
	v_mul_f32_e32 v118, v118, v177
	v_mul_f32_e32 v119, v119, v145
	v_mul_f32_e32 v127, v112, v191
	v_mul_f32_e32 v144, v113, v146
	v_mul_f32_e32 v145, v114, v193
	v_cvt_pk_bf16_f32 v112, v116, v117
	v_cvt_pk_bf16_f32 v113, v118, v119
	v_cvt_pk_bf16_f32 v114, v127, v144
	v_cvt_pk_bf16_f32 v115, v145, v115
	global_store_dwordx4 v[194:195], v[112:115], off
	v_ashrrev_i32_e32 v127, 31, v126
	v_lshlrev_b64 v[114:115], 13, v[126:127]
	v_or_b32_e32 v144, 48, v176
	v_lshl_add_u64 v[114:115], s[6:7], 0, v[114:115]
	v_mad_i64_i32 v[112:113], s[2:3], v144, s49, v[178:179]
	v_lshl_add_u64 v[114:115], v[114:115], 0, s[10:11]
	v_lshl_add_u64 v[112:113], v[112:113], 0, s[8:9]
	v_lshl_add_u64 v[146:147], v[114:115], 0, v[174:175]
	v_lshl_add_u64 v[126:127], v[112:113], 0, v[174:175]
	s_waitcnt vmcnt(8)
	v_mov_b32_e32 v116, v210
	v_mov_b32_e32 v117, v211
	v_mov_b32_e32 v118, v212
	v_mov_b32_e32 v119, v213
	s_mov_b32 s60, 0xd4100
	s_mov_b32 s61, 0
	v_lshl_add_u64 v[210:211], v[254:255], 0, s[60:61]
	global_load_dwordx4 v[210:213], v[210:211], off nt
	v_lshlrev_b32_e32 v183, 16, v119
	v_and_b32_e32 v119, 0xffff0000, v119
	v_lshlrev_b32_e32 v145, 16, v116
	v_and_b32_e32 v116, 0xffff0000, v116
	v_lshlrev_b32_e32 v177, 16, v117
	v_and_b32_e32 v117, 0xffff0000, v117
	v_lshlrev_b32_e32 v182, 16, v118
	v_and_b32_e32 v118, 0xffff0000, v118
	v_mul_f32_e32 v199, 0xbfb8aa3b, v119
	v_mul_f32_e32 v191, 0xbfb8aa3b, v145
	v_mul_f32_e32 v193, 0xbfb8aa3b, v116
	v_mul_f32_e32 v194, 0xbfb8aa3b, v177
	v_mul_f32_e32 v195, 0xbfb8aa3b, v117
	v_mul_f32_e32 v196, 0xbfb8aa3b, v182
	v_mul_f32_e32 v197, 0xbfb8aa3b, v118
	v_mul_f32_e32 v198, 0xbfb8aa3b, v183
	v_exp_f32_e32 v199, v199
	v_exp_f32_e32 v191, v191
	v_exp_f32_e32 v193, v193
	v_exp_f32_e32 v194, v194
	v_exp_f32_e32 v195, v195
	v_exp_f32_e32 v196, v196
	v_exp_f32_e32 v197, v197
	v_exp_f32_e32 v198, v198
	v_add_f32_e32 v199, 1.0, v199
	v_add_f32_e32 v191, 1.0, v191
	v_add_f32_e32 v193, 1.0, v193
	v_add_f32_e32 v194, 1.0, v194
	v_add_f32_e32 v195, 1.0, v195
	v_add_f32_e32 v196, 1.0, v196
	v_add_f32_e32 v197, 1.0, v197
	v_add_f32_e32 v198, 1.0, v198
	v_rcp_f32_e32 v199, v199
	v_rcp_f32_e32 v191, v191
	v_rcp_f32_e32 v193, v193
	v_rcp_f32_e32 v194, v194
	v_rcp_f32_e32 v195, v195
	v_rcp_f32_e32 v196, v196
	v_rcp_f32_e32 v197, v197
	v_rcp_f32_e32 v198, v198
	v_mul_f32_e32 v119, v199, v119
	v_mul_f32_e32 v145, v191, v145
	v_mul_f32_e32 v116, v193, v116
	v_mul_f32_e32 v177, v194, v177
	v_mul_f32_e32 v117, v195, v117
	v_mul_f32_e32 v182, v196, v182
	v_mul_f32_e32 v118, v197, v118
	v_mul_f32_e32 v183, v198, v183
	v_mul_f32_e32 v107, v107, v119
	v_mul_f32_e32 v108, v108, v145
	v_mul_f32_e32 v109, v109, v116
	v_mul_f32_e32 v110, v110, v177
	v_mul_f32_e32 v111, v111, v117
	v_mul_f32_e32 v116, v104, v182
	v_mul_f32_e32 v117, v105, v118
	v_mul_f32_e32 v118, v106, v183
	v_cvt_pk_bf16_f32 v104, v108, v109
	v_cvt_pk_bf16_f32 v105, v110, v111
	v_cvt_pk_bf16_f32 v106, v116, v117
	v_cvt_pk_bf16_f32 v107, v118, v107
	global_store_dwordx4 v[146:147], v[104:107], off
	v_ashrrev_i32_e32 v145, 31, v144
	v_lshlrev_b64 v[106:107], 13, v[144:145]
	v_add_u32_e32 v116, 0x80, v176
	v_lshl_add_u64 v[106:107], s[6:7], 0, v[106:107]
	v_mad_i64_i32 v[104:105], s[2:3], v116, s49, v[178:179]
	v_lshl_add_u64 v[106:107], v[106:107], 0, s[10:11]
	v_lshl_add_u64 v[104:105], v[104:105], 0, s[8:9]
	v_lshl_add_u64 v[126:127], v[106:107], 0, v[174:175]
	v_lshl_add_u64 v[118:119], v[104:105], 0, v[174:175]
	s_waitcnt vmcnt(9)
; __device__ __forceinline__ float bflo(unsigned w) { return __uint_as_float(w << 16); }
; __device__ __forceinline__ float bfhi(unsigned w) { return __uint_as_float(w & 0xffff0000u); }
; __device__ __forceinline__ unsigned pk2(float lo, float hi) { unsigned r; asm("v_cvt_pk_bf16_f32 %0, %1, %2" : "=v"(r) : "v"(lo), "v"(hi)); return r; }
; __device__ __forceinline__ float siluf_(float x) { return x * __builtin_amdgcn_rcpf(1.0f + __expf(-x)); }
;     __device__ __forceinline__ void operator()(const f32x4 (&acc)[2][2][4][2], const Unit& u, int wr, int wc, int fr, int fq) const {
;         const int row0 = u.pm * BM + wr * 64 + fr, col0 = u.pn * BM + wc * 32 + 8 * fq;
; #pragma unroll
;         for (int bj = 0; bj < 2; ++bj) { const int col = col0 + bj * HALF;
;             const f32x4 b0 = *(const f32x4*)(bias + col), b1 = *(const f32x4*)(bias + col + 4), s0 = *(const f32x4*)(scale + col), s1 = *(const f32x4*)(scale + col + 4);
; #pragma unroll
;             for (int ai = 0; ai < 2; ++ai)
; #pragma unroll
;                 for (int m = 0; m < 4; ++m) { const int row = row0 + ai * HALF + m * 16;
;                     const u32x4 z = __builtin_nontemporal_load((const u32x4*)(proj + (size_t)row * NPROJ + C_ZP + col));
;                     f32x4 v0 = (acc[ai][bj][m][0] + b0) * s0, v1 = (acc[ai][bj][m][1] + b1) * s1;
;                     v0[0] *= siluf_(bflo(z.x)); v0[1] *= siluf_(bfhi(z.x)); v0[2] *= siluf_(bflo(z.y)); v0[3] *= siluf_(bfhi(z.y));
;                     v1[0] *= siluf_(bflo(z.z)); v1[1] *= siluf_(bfhi(z.z)); v1[2] *= siluf_(bflo(z.w)); v1[3] *= siluf_(bfhi(z.w));
;                     u32x4 w; w.x = pk2(v0[0], v0[1]); w.y = pk2(v0[2], v0[3]); w.z = pk2(v1[0], v1[1]); w.w = pk2(v1[2], v1[3]);
;                     *(u32x4*)(a2 + (size_t)row * 4096 + 2048 + col) = w; } }
;     }
	v_mov_b32_e32 v108, v214
	v_mov_b32_e32 v109, v215
	v_mov_b32_e32 v110, v216
	v_mov_b32_e32 v111, v217
	s_mov_b32 s60, 0x13e100
	s_mov_b32 s61, 0
	v_lshl_add_u64 v[214:215], v[254:255], 0, s[60:61]
	global_load_dwordx4 v[214:217], v[214:215], off nt
	v_lshlrev_b32_e32 v146, 16, v111
	v_and_b32_e32 v111, 0xffff0000, v111
	v_lshlrev_b32_e32 v117, 16, v108
	v_and_b32_e32 v108, 0xffff0000, v108
	v_lshlrev_b32_e32 v144, 16, v109
	v_and_b32_e32 v109, 0xffff0000, v109
	v_lshlrev_b32_e32 v145, 16, v110
	v_and_b32_e32 v110, 0xffff0000, v110
	v_mul_f32_e32 v195, 0xbfb8aa3b, v111
	v_mul_f32_e32 v147, 0xbfb8aa3b, v117
	v_mul_f32_e32 v177, 0xbfb8aa3b, v108
	v_mul_f32_e32 v182, 0xbfb8aa3b, v144
	v_mul_f32_e32 v183, 0xbfb8aa3b, v109
	v_mul_f32_e32 v191, 0xbfb8aa3b, v145
	v_mul_f32_e32 v193, 0xbfb8aa3b, v110
	v_mul_f32_e32 v194, 0xbfb8aa3b, v146
	v_exp_f32_e32 v195, v195
	v_exp_f32_e32 v147, v147
	v_exp_f32_e32 v177, v177
	v_exp_f32_e32 v182, v182
	v_exp_f32_e32 v183, v183
	v_exp_f32_e32 v191, v191
	v_exp_f32_e32 v193, v193
	v_exp_f32_e32 v194, v194
	v_add_f32_e32 v195, 1.0, v195
	v_add_f32_e32 v147, 1.0, v147
	v_add_f32_e32 v177, 1.0, v177
	v_add_f32_e32 v182, 1.0, v182
	v_add_f32_e32 v183, 1.0, v183
	v_add_f32_e32 v191, 1.0, v191
	v_add_f32_e32 v193, 1.0, v193
	v_add_f32_e32 v194, 1.0, v194
	v_rcp_f32_e32 v195, v195
	v_rcp_f32_e32 v147, v147
	v_rcp_f32_e32 v177, v177
	v_rcp_f32_e32 v182, v182
	v_rcp_f32_e32 v183, v183
	v_rcp_f32_e32 v191, v191
	v_rcp_f32_e32 v193, v193
	v_rcp_f32_e32 v194, v194
	v_mul_f32_e32 v111, v195, v111
	v_mul_f32_e32 v117, v147, v117
	v_mul_f32_e32 v108, v177, v108
	v_mul_f32_e32 v144, v182, v144
	v_mul_f32_e32 v109, v183, v109
	v_mul_f32_e32 v145, v191, v145
	v_mul_f32_e32 v110, v193, v110
	v_mul_f32_e32 v146, v194, v146
	v_mul_f32_e32 v99, v99, v111
	v_mul_f32_e32 v100, v100, v117
	v_mul_f32_e32 v101, v101, v108
	v_mul_f32_e32 v102, v102, v144
	v_mul_f32_e32 v103, v103, v109
	v_mul_f32_e32 v108, v96, v145
	v_mul_f32_e32 v109, v97, v110
	v_mul_f32_e32 v110, v98, v146
	v_cvt_pk_bf16_f32 v96, v100, v101
	v_cvt_pk_bf16_f32 v97, v102, v103
	v_cvt_pk_bf16_f32 v98, v108, v109
	v_cvt_pk_bf16_f32 v99, v110, v99
	global_store_dwordx4 v[126:127], v[96:99], off
	v_ashrrev_i32_e32 v117, 31, v116
	v_lshlrev_b64 v[98:99], 13, v[116:117]
	v_add_u32_e32 v108, 0x90, v176
	v_lshl_add_u64 v[98:99], s[6:7], 0, v[98:99]
	v_mad_i64_i32 v[96:97], s[2:3], v108, s49, v[178:179]
	v_lshl_add_u64 v[98:99], v[98:99], 0, s[10:11]
	v_lshl_add_u64 v[96:97], v[96:97], 0, s[8:9]
	v_lshl_add_u64 v[116:117], v[98:99], 0, v[174:175]
	v_lshl_add_u64 v[110:111], v[96:97], 0, v[174:175]
	s_waitcnt vmcnt(10)
	v_mov_b32_e32 v100, v218
	v_mov_b32_e32 v101, v219
	v_mov_b32_e32 v102, v220
	v_mov_b32_e32 v103, v221
	s_mov_b32 s60, 0x350100
	s_mov_b32 s61, 0
	v_lshl_add_u64 v[218:219], v[254:255], 0, s[60:61]
	global_load_dwordx4 v[218:221], v[218:219], off nt
	v_lshlrev_b32_e32 v126, 16, v103
	v_and_b32_e32 v103, 0xffff0000, v103
	v_lshlrev_b32_e32 v109, 16, v100
	v_and_b32_e32 v100, 0xffff0000, v100
	v_lshlrev_b32_e32 v118, 16, v101
	v_and_b32_e32 v101, 0xffff0000, v101
	v_lshlrev_b32_e32 v119, 16, v102
	v_and_b32_e32 v102, 0xffff0000, v102
	v_mul_f32_e32 v183, 0xbfb8aa3b, v103
	v_mul_f32_e32 v127, 0xbfb8aa3b, v109
	v_mul_f32_e32 v144, 0xbfb8aa3b, v100
	v_mul_f32_e32 v145, 0xbfb8aa3b, v118
	v_mul_f32_e32 v146, 0xbfb8aa3b, v101
	v_mul_f32_e32 v147, 0xbfb8aa3b, v119
	v_mul_f32_e32 v177, 0xbfb8aa3b, v102
	v_mul_f32_e32 v182, 0xbfb8aa3b, v126
	v_exp_f32_e32 v183, v183
	v_exp_f32_e32 v127, v127
	v_exp_f32_e32 v144, v144
	v_exp_f32_e32 v145, v145
	v_exp_f32_e32 v146, v146
	v_exp_f32_e32 v147, v147
	v_exp_f32_e32 v177, v177
	v_exp_f32_e32 v182, v182
	v_add_f32_e32 v183, 1.0, v183
	v_add_f32_e32 v127, 1.0, v127
	v_add_f32_e32 v144, 1.0, v144
	v_add_f32_e32 v145, 1.0, v145
	v_add_f32_e32 v146, 1.0, v146
	v_add_f32_e32 v147, 1.0, v147
	v_add_f32_e32 v177, 1.0, v177
	v_add_f32_e32 v182, 1.0, v182
	v_rcp_f32_e32 v183, v183
	v_rcp_f32_e32 v127, v127
	v_rcp_f32_e32 v144, v144
	v_rcp_f32_e32 v145, v145
	v_rcp_f32_e32 v146, v146
	v_rcp_f32_e32 v147, v147
	v_rcp_f32_e32 v177, v177
	v_rcp_f32_e32 v182, v182
	v_mul_f32_e32 v103, v183, v103
	v_mul_f32_e32 v109, v127, v109
	v_mul_f32_e32 v100, v144, v100
	v_mul_f32_e32 v118, v145, v118
	v_mul_f32_e32 v101, v146, v101
	v_mul_f32_e32 v119, v147, v119
	v_mul_f32_e32 v102, v177, v102
	v_mul_f32_e32 v126, v182, v126
	v_mul_f32_e32 v91, v91, v103
	v_mul_f32_e32 v92, v92, v109
	v_mul_f32_e32 v93, v93, v100
	v_mul_f32_e32 v94, v94, v118
	v_mul_f32_e32 v95, v95, v101
	v_mul_f32_e32 v100, v88, v119
	v_mul_f32_e32 v101, v89, v102
	v_mul_f32_e32 v102, v90, v126
	v_cvt_pk_bf16_f32 v88, v92, v93
	v_cvt_pk_bf16_f32 v89, v94, v95
	v_cvt_pk_bf16_f32 v90, v100, v101
	v_cvt_pk_bf16_f32 v91, v102, v91
	global_store_dwordx4 v[116:117], v[88:91], off
	v_ashrrev_i32_e32 v109, 31, v108
	v_lshlrev_b64 v[90:91], 13, v[108:109]
	v_add_u32_e32 v100, 0xa0, v176
	v_lshl_add_u64 v[90:91], s[6:7], 0, v[90:91]
	v_mad_i64_i32 v[88:89], s[2:3], v100, s49, v[178:179]
	v_lshl_add_u64 v[90:91], v[90:91], 0, s[10:11]
	v_lshl_add_u64 v[88:89], v[88:89], 0, s[8:9]
	v_lshl_add_u64 v[108:109], v[90:91], 0, v[174:175]
	v_lshl_add_u64 v[102:103], v[88:89], 0, v[174:175]
	s_waitcnt vmcnt(11)
; __device__ __forceinline__ float bflo(unsigned w) { return __uint_as_float(w << 16); }
; __device__ __forceinline__ float bfhi(unsigned w) { return __uint_as_float(w & 0xffff0000u); }
; __device__ __forceinline__ unsigned pk2(float lo, float hi) { unsigned r; asm("v_cvt_pk_bf16_f32 %0, %1, %2" : "=v"(r) : "v"(lo), "v"(hi)); return r; }
; __device__ __forceinline__ float siluf_(float x) { return x * __builtin_amdgcn_rcpf(1.0f + __expf(-x)); }
;     __device__ __forceinline__ void operator()(const f32x4 (&acc)[2][2][4][2], const Unit& u, int wr, int wc, int fr, int fq) const {
;         const int row0 = u.pm * BM + wr * 64 + fr, col0 = u.pn * BM + wc * 32 + 8 * fq;
; #pragma unroll
;         for (int bj = 0; bj < 2; ++bj) { const int col = col0 + bj * HALF;
;             const f32x4 b0 = *(const f32x4*)(bias + col), b1 = *(const f32x4*)(bias + col + 4), s0 = *(const f32x4*)(scale + col), s1 = *(const f32x4*)(scale + col + 4);
; #pragma unroll
;             for (int ai = 0; ai < 2; ++ai)
; #pragma unroll
;                 for (int m = 0; m < 4; ++m) { const int row = row0 + ai * HALF + m * 16;
;                     const u32x4 z = __builtin_nontemporal_load((const u32x4*)(proj + (size_t)row * NPROJ + C_ZP + col));
;                     f32x4 v0 = (acc[ai][bj][m][0] + b0) * s0, v1 = (acc[ai][bj][m][1] + b1) * s1;
;                     v0[0] *= siluf_(bflo(z.x)); v0[1] *= siluf_(bfhi(z.x)); v0[2] *= siluf_(bflo(z.y)); v0[3] *= siluf_(bfhi(z.y));
;                     v1[0] *= siluf_(bflo(z.z)); v1[1] *= siluf_(bfhi(z.z)); v1[2] *= siluf_(bflo(z.w)); v1[3] *= siluf_(bfhi(z.w));
;                     u32x4 w; w.x = pk2(v0[0], v0[1]); w.y = pk2(v0[2], v0[3]); w.z = pk2(v1[0], v1[1]); w.w = pk2(v1[2], v1[3]);
;                     *(u32x4*)(a2 + (size_t)row * 4096 + 2048 + col) = w; } }
;     }
	v_mov_b32_e32 v92, v222
	v_mov_b32_e32 v93, v223
	v_mov_b32_e32 v94, v224
	v_mov_b32_e32 v95, v225
	s_mov_b32 s60, 0x3ba100
	s_mov_b32 s61, 0
	v_lshl_add_u64 v[222:223], v[254:255], 0, s[60:61]
	global_load_dwordx4 v[222:225], v[222:223], off nt
	v_lshlrev_b32_e32 v116, 16, v95
	v_and_b32_e32 v95, 0xffff0000, v95
	v_lshlrev_b32_e32 v101, 16, v92
	v_and_b32_e32 v92, 0xffff0000, v92
	v_lshlrev_b32_e32 v110, 16, v93
	v_and_b32_e32 v93, 0xffff0000, v93
	v_lshlrev_b32_e32 v111, 16, v94
	v_and_b32_e32 v94, 0xffff0000, v94
	v_mul_f32_e32 v146, 0xbfb8aa3b, v95
	v_mul_f32_e32 v117, 0xbfb8aa3b, v101
	v_mul_f32_e32 v118, 0xbfb8aa3b, v92
	v_mul_f32_e32 v119, 0xbfb8aa3b, v110
	v_mul_f32_e32 v126, 0xbfb8aa3b, v93
	v_mul_f32_e32 v127, 0xbfb8aa3b, v111
	v_mul_f32_e32 v144, 0xbfb8aa3b, v94
	v_mul_f32_e32 v145, 0xbfb8aa3b, v116
	v_exp_f32_e32 v146, v146
	v_exp_f32_e32 v117, v117
	v_exp_f32_e32 v118, v118
	v_exp_f32_e32 v119, v119
	v_exp_f32_e32 v126, v126
	v_exp_f32_e32 v127, v127
	v_exp_f32_e32 v144, v144
	v_exp_f32_e32 v145, v145
	v_add_f32_e32 v146, 1.0, v146
	v_add_f32_e32 v117, 1.0, v117
	v_add_f32_e32 v118, 1.0, v118
	v_add_f32_e32 v119, 1.0, v119
	v_add_f32_e32 v126, 1.0, v126
	v_add_f32_e32 v127, 1.0, v127
	v_add_f32_e32 v144, 1.0, v144
	v_add_f32_e32 v145, 1.0, v145
	v_rcp_f32_e32 v146, v146
	v_rcp_f32_e32 v117, v117
	v_rcp_f32_e32 v118, v118
	v_rcp_f32_e32 v119, v119
	v_rcp_f32_e32 v126, v126
	v_rcp_f32_e32 v127, v127
	v_rcp_f32_e32 v144, v144
	v_rcp_f32_e32 v145, v145
	v_mul_f32_e32 v95, v146, v95
	v_mul_f32_e32 v101, v117, v101
	v_mul_f32_e32 v92, v118, v92
	v_mul_f32_e32 v110, v119, v110
	v_mul_f32_e32 v93, v126, v93
	v_mul_f32_e32 v111, v127, v111
	v_mul_f32_e32 v94, v144, v94
	v_mul_f32_e32 v116, v145, v116
	v_mul_f32_e32 v83, v83, v95
	v_mul_f32_e32 v84, v84, v101
	v_mul_f32_e32 v85, v85, v92
	v_mul_f32_e32 v86, v86, v110
	v_mul_f32_e32 v87, v87, v93
	v_mul_f32_e32 v92, v80, v111
	v_mul_f32_e32 v93, v81, v94
	v_mul_f32_e32 v94, v82, v116
	v_cvt_pk_bf16_f32 v80, v84, v85
	v_cvt_pk_bf16_f32 v81, v86, v87
	v_cvt_pk_bf16_f32 v82, v92, v93
	v_cvt_pk_bf16_f32 v83, v94, v83
	global_store_dwordx4 v[108:109], v[80:83], off
	v_ashrrev_i32_e32 v101, 31, v100
	v_lshlrev_b64 v[84:85], 13, v[100:101]
	v_add_u32_e32 v80, 0xb0, v176
	v_lshl_add_u64 v[84:85], s[6:7], 0, v[84:85]
	v_mad_i64_i32 v[82:83], s[2:3], v80, s49, v[178:179]
	v_lshl_add_u64 v[84:85], v[84:85], 0, s[10:11]
	v_lshl_add_u64 v[82:83], v[82:83], 0, s[8:9]
	v_lshl_add_u64 v[100:101], v[84:85], 0, v[174:175]
	v_lshl_add_u64 v[86:87], v[82:83], 0, v[174:175]
	s_waitcnt vmcnt(12)
	v_mov_b32_e32 v92, v226
	v_mov_b32_e32 v93, v227
	v_mov_b32_e32 v94, v228
	v_mov_b32_e32 v95, v229
	s_mov_b32 s60, 0x424100
	s_mov_b32 s61, 0
	v_lshl_add_u64 v[226:227], v[254:255], 0, s[60:61]
	global_load_dwordx4 v[226:229], v[226:227], off nt
	v_lshlrev_b32_e32 v108, 16, v95
	v_and_b32_e32 v95, 0xffff0000, v95
	v_lshlrev_b32_e32 v81, 16, v92
	v_and_b32_e32 v92, 0xffff0000, v92
	v_lshlrev_b32_e32 v102, 16, v93
	v_and_b32_e32 v93, 0xffff0000, v93
	v_lshlrev_b32_e32 v103, 16, v94
	v_and_b32_e32 v94, 0xffff0000, v94
	v_mul_f32_e32 v126, 0xbfb8aa3b, v95
	v_mul_f32_e32 v109, 0xbfb8aa3b, v81
	v_mul_f32_e32 v110, 0xbfb8aa3b, v92
	v_mul_f32_e32 v111, 0xbfb8aa3b, v102
	v_mul_f32_e32 v116, 0xbfb8aa3b, v93
	v_mul_f32_e32 v117, 0xbfb8aa3b, v103
	v_mul_f32_e32 v118, 0xbfb8aa3b, v94
	v_mul_f32_e32 v119, 0xbfb8aa3b, v108
	v_exp_f32_e32 v126, v126
	v_exp_f32_e32 v109, v109
	v_exp_f32_e32 v110, v110
	v_exp_f32_e32 v111, v111
	v_exp_f32_e32 v116, v116
	v_exp_f32_e32 v117, v117
	v_exp_f32_e32 v118, v118
	v_exp_f32_e32 v119, v119
	v_add_f32_e32 v126, 1.0, v126
	v_add_f32_e32 v109, 1.0, v109
	v_add_f32_e32 v110, 1.0, v110
	v_add_f32_e32 v111, 1.0, v111
	v_add_f32_e32 v116, 1.0, v116
	v_add_f32_e32 v117, 1.0, v117
	v_add_f32_e32 v118, 1.0, v118
	v_add_f32_e32 v119, 1.0, v119
	v_rcp_f32_e32 v126, v126
	v_rcp_f32_e32 v109, v109
	v_rcp_f32_e32 v110, v110
	v_rcp_f32_e32 v111, v111
	v_rcp_f32_e32 v116, v116
	v_rcp_f32_e32 v117, v117
	v_rcp_f32_e32 v118, v118
	v_rcp_f32_e32 v119, v119
	v_mul_f32_e32 v95, v126, v95
	v_mul_f32_e32 v81, v109, v81
	v_mul_f32_e32 v92, v110, v92
	v_mul_f32_e32 v102, v111, v102
	v_mul_f32_e32 v93, v116, v93
	v_mul_f32_e32 v103, v117, v103
	v_mul_f32_e32 v94, v118, v94
	v_mul_f32_e32 v108, v119, v108
	v_mul_f32_e32 v75, v75, v95
	v_mul_f32_e32 v76, v76, v81
	v_mul_f32_e32 v77, v77, v92
	v_mul_f32_e32 v78, v78, v102
	v_mul_f32_e32 v79, v79, v93
	v_mul_f32_e32 v81, v72, v103
	v_mul_f32_e32 v92, v73, v94
	v_mul_f32_e32 v93, v74, v108
	v_cvt_pk_bf16_f32 v72, v76, v77
	v_cvt_pk_bf16_f32 v73, v78, v79
	v_cvt_pk_bf16_f32 v74, v81, v92
	v_cvt_pk_bf16_f32 v75, v93, v75
	global_store_dwordx4 v[100:101], v[72:75], off
	v_ashrrev_i32_e32 v81, 31, v80
	v_lshlrev_b64 v[76:77], 13, v[80:81]
	v_lshl_add_u64 v[76:77], s[6:7], 0, v[76:77]
	v_lshl_add_u64 v[80:81], v[76:77], 0, s[10:11]
	v_lshl_add_u64 v[76:77], v[80:81], 0, v[174:175]
	v_and_b32_e32 v109, 0xffff0000, v151
	v_lshlrev_b32_e32 v108, 16, v151
	s_waitcnt vmcnt(13)
; __device__ __forceinline__ float bflo(unsigned w) { return __uint_as_float(w << 16); }
; __device__ __forceinline__ float bfhi(unsigned w) { return __uint_as_float(w & 0xffff0000u); }
; __device__ __forceinline__ unsigned pk2(float lo, float hi) { unsigned r; asm("v_cvt_pk_bf16_f32 %0, %1, %2" : "=v"(r) : "v"(lo), "v"(hi)); return r; }
; __device__ __forceinline__ float siluf_(float x) { return x * __builtin_amdgcn_rcpf(1.0f + __expf(-x)); }
;     __device__ __forceinline__ void operator()(const f32x4 (&acc)[2][2][4][2], const Unit& u, int wr, int wc, int fr, int fq) const {
;         const int row0 = u.pm * BM + wr * 64 + fr, col0 = u.pn * BM + wc * 32 + 8 * fq;
; #pragma unroll
;         for (int bj = 0; bj < 2; ++bj) { const int col = col0 + bj * HALF;
;             const f32x4 b0 = *(const f32x4*)(bias + col), b1 = *(const f32x4*)(bias + col + 4), s0 = *(const f32x4*)(scale + col), s1 = *(const f32x4*)(scale + col + 4);
; #pragma unroll
;             for (int ai = 0; ai < 2; ++ai)
; #pragma unroll
;                 for (int m = 0; m < 4; ++m) { const int row = row0 + ai * HALF + m * 16;
;                     const u32x4 z = __builtin_nontemporal_load((const u32x4*)(proj + (size_t)row * NPROJ + C_ZP + col));
;                     f32x4 v0 = (acc[ai][bj][m][0] + b0) * s0, v1 = (acc[ai][bj][m][1] + b1) * s1;
;                     v0[0] *= siluf_(bflo(z.x)); v0[1] *= siluf_(bfhi(z.x)); v0[2] *= siluf_(bflo(z.y)); v0[3] *= siluf_(bfhi(z.y));
;                     v1[0] *= siluf_(bflo(z.z)); v1[1] *= siluf_(bfhi(z.z)); v1[2] *= siluf_(bflo(z.w)); v1[3] *= siluf_(bfhi(z.w));
;                     u32x4 w; w.x = pk2(v0[0], v0[1]); w.y = pk2(v0[2], v0[3]); w.z = pk2(v1[0], v1[1]); w.w = pk2(v1[2], v1[3]);
;                     *(u32x4*)(a2 + (size_t)row * 4096 + 2048 + col) = w; } }
;     }
	v_mov_b32_e32 v72, v230
	v_mov_b32_e32 v73, v231
	v_mov_b32_e32 v74, v232
	v_mov_b32_e32 v75, v233
	s_mov_b32 s60, 0x48e100
	s_mov_b32 s61, 0
	v_lshl_add_u64 v[230:231], v[254:255], 0, s[60:61]
	global_load_dwordx4 v[230:233], v[230:231], off nt
	v_lshlrev_b32_e32 v87, 16, v75
	v_and_b32_e32 v75, 0xffff0000, v75
	v_lshlrev_b32_e32 v78, 16, v72
	v_and_b32_e32 v72, 0xffff0000, v72
	v_lshlrev_b32_e32 v79, 16, v73
	v_and_b32_e32 v73, 0xffff0000, v73
	v_lshlrev_b32_e32 v86, 16, v74
	v_and_b32_e32 v74, 0xffff0000, v74
	v_mul_f32_e32 v103, 0xbfb8aa3b, v75
	v_mul_f32_e32 v92, 0xbfb8aa3b, v78
	v_mul_f32_e32 v93, 0xbfb8aa3b, v72
	v_mul_f32_e32 v94, 0xbfb8aa3b, v79
	v_mul_f32_e32 v95, 0xbfb8aa3b, v73
	v_mul_f32_e32 v100, 0xbfb8aa3b, v86
	v_mul_f32_e32 v101, 0xbfb8aa3b, v74
	v_mul_f32_e32 v102, 0xbfb8aa3b, v87
	v_exp_f32_e32 v103, v103
	v_exp_f32_e32 v92, v92
	v_exp_f32_e32 v93, v93
	v_exp_f32_e32 v94, v94
	v_exp_f32_e32 v95, v95
	v_exp_f32_e32 v100, v100
	v_exp_f32_e32 v101, v101
	v_exp_f32_e32 v102, v102
	v_add_f32_e32 v103, 1.0, v103
	v_add_f32_e32 v92, 1.0, v92
	v_add_f32_e32 v93, 1.0, v93
	v_add_f32_e32 v94, 1.0, v94
	v_add_f32_e32 v95, 1.0, v95
	v_add_f32_e32 v100, 1.0, v100
	v_add_f32_e32 v101, 1.0, v101
	v_add_f32_e32 v102, 1.0, v102
	v_rcp_f32_e32 v103, v103
	v_rcp_f32_e32 v92, v92
	v_rcp_f32_e32 v93, v93
	v_rcp_f32_e32 v94, v94
	v_rcp_f32_e32 v95, v95
	v_rcp_f32_e32 v100, v100
	v_rcp_f32_e32 v101, v101
	v_rcp_f32_e32 v102, v102
	v_mul_f32_e32 v75, v103, v75
	v_mul_f32_e32 v78, v92, v78
	v_mul_f32_e32 v72, v93, v72
	v_mul_f32_e32 v79, v94, v79
	v_mul_f32_e32 v73, v95, v73
	v_mul_f32_e32 v86, v100, v86
	v_mul_f32_e32 v74, v101, v74
	v_mul_f32_e32 v87, v102, v87
	v_mul_f32_e32 v67, v67, v75
	v_mul_f32_e32 v68, v68, v78
	v_mul_f32_e32 v69, v69, v72
	v_mul_f32_e32 v70, v70, v79
	v_mul_f32_e32 v71, v71, v73
	v_mul_f32_e32 v72, v64, v86
	v_mul_f32_e32 v73, v65, v74
	v_mul_f32_e32 v74, v66, v87
	v_cvt_pk_bf16_f32 v64, v68, v69
	v_cvt_pk_bf16_f32 v65, v70, v71
	v_cvt_pk_bf16_f32 v66, v72, v73
	v_cvt_pk_bf16_f32 v67, v74, v67
	global_store_dwordx4 v[76:77], v[64:67], off
	v_mov_b32_e32 v76, v234
	v_mov_b32_e32 v77, v235
	v_mov_b32_e32 v78, v236
	v_mov_b32_e32 v79, v237
	s_nop 0
	v_mov_b32_e32 v72, v238
	v_mov_b32_e32 v73, v239
	v_mov_b32_e32 v74, v240
	v_mov_b32_e32 v75, v241
	v_mov_b32_e32 v68, v246
	v_mov_b32_e32 v69, v247
	v_mov_b32_e32 v70, v248
	v_mov_b32_e32 v71, v249
	v_mov_b32_e32 v64, v250
	v_mov_b32_e32 v65, v251
	v_mov_b32_e32 v66, v252
	v_mov_b32_e32 v67, v253
	v_lshl_add_u64 v[86:87], v[124:125], 0, v[168:169]
	v_lshlrev_b32_e32 v94, 16, v148
	v_and_b32_e32 v95, 0xffff0000, v148
	v_lshlrev_b32_e32 v100, 16, v149
	v_and_b32_e32 v101, 0xffff0000, v149
	v_lshlrev_b32_e32 v102, 16, v150
	v_and_b32_e32 v103, 0xffff0000, v150
	v_mul_f32_e32 v125, 0xbfb8aa3b, v109
	v_mul_f32_e32 v110, 0xbfb8aa3b, v94
	v_mul_f32_e32 v111, 0xbfb8aa3b, v95
	v_mul_f32_e32 v116, 0xbfb8aa3b, v100
	v_mul_f32_e32 v117, 0xbfb8aa3b, v101
	v_mul_f32_e32 v118, 0xbfb8aa3b, v102
	v_mul_f32_e32 v119, 0xbfb8aa3b, v103
	v_mul_f32_e32 v124, 0xbfb8aa3b, v108
	v_exp_f32_e32 v125, v125
	v_exp_f32_e32 v110, v110
	v_exp_f32_e32 v111, v111
	v_exp_f32_e32 v116, v116
	v_exp_f32_e32 v117, v117
	v_exp_f32_e32 v118, v118
	v_exp_f32_e32 v119, v119
	v_exp_f32_e32 v124, v124
	v_add_f32_e32 v125, 1.0, v125
	v_add_f32_e32 v110, 1.0, v110
	v_add_f32_e32 v111, 1.0, v111
	v_add_f32_e32 v116, 1.0, v116
	v_add_f32_e32 v117, 1.0, v117
	v_add_f32_e32 v118, 1.0, v118
	v_add_f32_e32 v119, 1.0, v119
	v_add_f32_e32 v124, 1.0, v124
	v_rcp_f32_e32 v125, v125
	v_rcp_f32_e32 v110, v110
	v_rcp_f32_e32 v111, v111
	v_rcp_f32_e32 v116, v116
	v_rcp_f32_e32 v117, v117
	v_rcp_f32_e32 v118, v118
	v_rcp_f32_e32 v119, v119
	v_rcp_f32_e32 v124, v124
	v_mul_f32_e32 v109, v125, v109
	v_lshl_add_u64 v[92:93], v[180:181], 0, v[168:169]
	v_mul_f32_e32 v94, v110, v94
	v_mul_f32_e32 v95, v111, v95
	v_mul_f32_e32 v100, v116, v100
	v_mul_f32_e32 v101, v117, v101
	v_mul_f32_e32 v102, v118, v102
	v_mul_f32_e32 v103, v119, v103
	v_mul_f32_e32 v108, v124, v108
	s_nop 0
	v_pk_add_f32 v[62:63], v[62:63], v[78:79]
	v_pk_add_f32 v[58:59], v[58:59], v[74:75]
	v_pk_add_f32 v[60:61], v[60:61], v[76:77]
	v_pk_add_f32 v[56:57], v[56:57], v[72:73]
	v_pk_mul_f32 v[58:59], v[58:59], v[66:67]
	v_pk_mul_f32 v[62:63], v[62:63], v[70:71]
	v_pk_mul_f32 v[60:61], v[60:61], v[68:69]
	v_pk_mul_f32 v[56:57], v[56:57], v[64:65]
	v_mul_f32_e32 v59, v59, v109
	v_mul_f32_e32 v60, v60, v94
	v_mul_f32_e32 v61, v61, v95
	v_mul_f32_e32 v62, v62, v100
	v_mul_f32_e32 v63, v63, v101
	v_mul_f32_e32 v94, v56, v102
	v_mul_f32_e32 v95, v57, v103
	v_mul_f32_e32 v100, v58, v108
	v_cvt_pk_bf16_f32 v56, v60, v61
	v_cvt_pk_bf16_f32 v57, v62, v63
	v_cvt_pk_bf16_f32 v58, v94, v95
	v_cvt_pk_bf16_f32 v59, v100, v59
	global_store_dwordx4 v[92:93], v[56:59], off
	v_pk_add_f32 v[50:51], v[50:51], v[74:75]
	v_pk_add_f32 v[54:55], v[54:55], v[78:79]
	v_pk_add_f32 v[52:53], v[52:53], v[76:77]
	v_pk_add_f32 v[48:49], v[48:49], v[72:73]
	v_pk_mul_f32 v[50:51], v[50:51], v[66:67]
	v_lshl_add_u64 v[62:63], v[122:123], 0, v[168:169]
	v_pk_mul_f32 v[54:55], v[54:55], v[70:71]
	v_pk_mul_f32 v[52:53], v[52:53], v[68:69]
	v_pk_mul_f32 v[48:49], v[48:49], v[64:65]
	v_lshl_add_u64 v[60:61], v[120:121], 0, v[168:169]
	v_pk_add_f32 v[42:43], v[42:43], v[74:75]
	v_pk_add_f32 v[46:47], v[46:47], v[78:79]
	v_pk_add_f32 v[44:45], v[44:45], v[76:77]
	v_pk_add_f32 v[40:41], v[40:41], v[72:73]
	v_pk_mul_f32 v[42:43], v[42:43], v[66:67]
	v_pk_mul_f32 v[46:47], v[46:47], v[70:71]
	v_pk_mul_f32 v[44:45], v[44:45], v[68:69]
	v_pk_mul_f32 v[40:41], v[40:41], v[64:65]
	v_pk_add_f32 v[34:35], v[34:35], v[74:75]
; __device__ __forceinline__ float bflo(unsigned w) { return __uint_as_float(w << 16); }
; __device__ __forceinline__ float bfhi(unsigned w) { return __uint_as_float(w & 0xffff0000u); }
; __device__ __forceinline__ unsigned pk2(float lo, float hi) { unsigned r; asm("v_cvt_pk_bf16_f32 %0, %1, %2" : "=v"(r) : "v"(lo), "v"(hi)); return r; }
; __device__ __forceinline__ float siluf_(float x) { return x * __builtin_amdgcn_rcpf(1.0f + __expf(-x)); }
;     __device__ __forceinline__ void operator()(const f32x4 (&acc)[2][2][4][2], const Unit& u, int wr, int wc, int fr, int fq) const {
;         const int row0 = u.pm * BM + wr * 64 + fr, col0 = u.pn * BM + wc * 32 + 8 * fq;
; #pragma unroll
;         for (int bj = 0; bj < 2; ++bj) { const int col = col0 + bj * HALF;
;             const f32x4 b0 = *(const f32x4*)(bias + col), b1 = *(const f32x4*)(bias + col + 4), s0 = *(const f32x4*)(scale + col), s1 = *(const f32x4*)(scale + col + 4);
; #pragma unroll
;             for (int ai = 0; ai < 2; ++ai)
; #pragma unroll
;                 for (int m = 0; m < 4; ++m) { const int row = row0 + ai * HALF + m * 16;
;                     const u32x4 z = __builtin_nontemporal_load((const u32x4*)(proj + (size_t)row * NPROJ + C_ZP + col));
;                     f32x4 v0 = (acc[ai][bj][m][0] + b0) * s0, v1 = (acc[ai][bj][m][1] + b1) * s1;
;                     v0[0] *= siluf_(bflo(z.x)); v0[1] *= siluf_(bfhi(z.x)); v0[2] *= siluf_(bflo(z.y)); v0[3] *= siluf_(bfhi(z.y));
;                     v1[0] *= siluf_(bflo(z.z)); v1[1] *= siluf_(bfhi(z.z)); v1[2] *= siluf_(bflo(z.w)); v1[3] *= siluf_(bfhi(z.w));
;                     u32x4 w; w.x = pk2(v0[0], v0[1]); w.y = pk2(v0[2], v0[3]); w.z = pk2(v1[0], v1[1]); w.w = pk2(v1[2], v1[3]);
;                     *(u32x4*)(a2 + (size_t)row * 4096 + 2048 + col) = w; } }
;     }
	v_pk_add_f32 v[38:39], v[38:39], v[78:79]
	v_pk_add_f32 v[36:37], v[36:37], v[76:77]
	v_pk_add_f32 v[32:33], v[32:33], v[72:73]
	v_pk_mul_f32 v[34:35], v[34:35], v[66:67]
	v_pk_mul_f32 v[38:39], v[38:39], v[70:71]
	v_pk_mul_f32 v[36:37], v[36:37], v[68:69]
	v_pk_mul_f32 v[32:33], v[32:33], v[64:65]
	v_pk_add_f32 v[26:27], v[26:27], v[74:75]
	v_pk_add_f32 v[30:31], v[30:31], v[78:79]
	v_pk_add_f32 v[28:29], v[28:29], v[76:77]
	v_pk_add_f32 v[24:25], v[24:25], v[72:73]
	v_pk_mul_f32 v[26:27], v[26:27], v[66:67]
	v_pk_mul_f32 v[30:31], v[30:31], v[70:71]
	v_pk_mul_f32 v[28:29], v[28:29], v[68:69]
	v_pk_mul_f32 v[24:25], v[24:25], v[64:65]
	v_pk_add_f32 v[18:19], v[18:19], v[74:75]
	v_pk_add_f32 v[22:23], v[22:23], v[78:79]
	v_pk_add_f32 v[20:21], v[20:21], v[76:77]
	v_pk_add_f32 v[16:17], v[16:17], v[72:73]
	v_pk_mul_f32 v[18:19], v[18:19], v[66:67]
	v_pk_mul_f32 v[22:23], v[22:23], v[70:71]
	v_pk_mul_f32 v[20:21], v[20:21], v[68:69]
	v_pk_mul_f32 v[16:17], v[16:17], v[64:65]
	v_pk_add_f32 v[10:11], v[10:11], v[74:75]
	v_pk_add_f32 v[14:15], v[14:15], v[78:79]
	v_pk_add_f32 v[12:13], v[12:13], v[76:77]
	v_pk_add_f32 v[8:9], v[8:9], v[72:73]
	v_pk_mul_f32 v[10:11], v[10:11], v[66:67]
	v_pk_mul_f32 v[14:15], v[14:15], v[70:71]
	v_pk_mul_f32 v[12:13], v[12:13], v[68:69]
	v_pk_mul_f32 v[8:9], v[8:9], v[64:65]
	v_pk_add_f32 v[2:3], v[2:3], v[74:75]
	v_pk_add_f32 v[6:7], v[6:7], v[78:79]
	v_pk_add_f32 v[4:5], v[4:5], v[76:77]
	v_pk_add_f32 v[0:1], v[0:1], v[72:73]
	v_pk_mul_f32 v[2:3], v[2:3], v[66:67]
	v_pk_mul_f32 v[6:7], v[6:7], v[70:71]
	v_pk_mul_f32 v[4:5], v[4:5], v[68:69]
	v_pk_mul_f32 v[0:1], v[0:1], v[64:65]
	s_waitcnt vmcnt(14)
	v_mov_b32_e32 v56, v206
	v_mov_b32_e32 v57, v207
	v_mov_b32_e32 v58, v208
	v_mov_b32_e32 v59, v209
	v_lshlrev_b32_e32 v93, 16, v59
	v_and_b32_e32 v59, 0xffff0000, v59
	v_lshlrev_b32_e32 v86, 16, v56
	v_and_b32_e32 v56, 0xffff0000, v56
	v_lshlrev_b32_e32 v87, 16, v57
	v_and_b32_e32 v57, 0xffff0000, v57
	v_lshlrev_b32_e32 v92, 16, v58
	v_and_b32_e32 v58, 0xffff0000, v58
	v_mul_f32_e32 v109, 0xbfb8aa3b, v59
	v_mul_f32_e32 v94, 0xbfb8aa3b, v86
	v_mul_f32_e32 v95, 0xbfb8aa3b, v56
	v_mul_f32_e32 v100, 0xbfb8aa3b, v87
	v_mul_f32_e32 v101, 0xbfb8aa3b, v57
	v_mul_f32_e32 v102, 0xbfb8aa3b, v92
	v_mul_f32_e32 v103, 0xbfb8aa3b, v58
	v_mul_f32_e32 v108, 0xbfb8aa3b, v93
	v_exp_f32_e32 v109, v109
	v_exp_f32_e32 v94, v94
	v_exp_f32_e32 v95, v95
	v_exp_f32_e32 v100, v100
	v_exp_f32_e32 v101, v101
	v_exp_f32_e32 v102, v102
	v_exp_f32_e32 v103, v103
	v_exp_f32_e32 v108, v108
	v_add_f32_e32 v109, 1.0, v109
	v_add_f32_e32 v94, 1.0, v94
	v_add_f32_e32 v95, 1.0, v95
	v_add_f32_e32 v100, 1.0, v100
	v_add_f32_e32 v101, 1.0, v101
	v_add_f32_e32 v102, 1.0, v102
	v_add_f32_e32 v103, 1.0, v103
	v_add_f32_e32 v108, 1.0, v108
	v_rcp_f32_e32 v109, v109
	v_rcp_f32_e32 v94, v94
	v_rcp_f32_e32 v95, v95
	v_rcp_f32_e32 v100, v100
	v_rcp_f32_e32 v101, v101
	v_rcp_f32_e32 v102, v102
	v_rcp_f32_e32 v103, v103
	v_rcp_f32_e32 v108, v108
	v_mul_f32_e32 v59, v109, v59
	v_mul_f32_e32 v86, v94, v86
	v_mul_f32_e32 v56, v95, v56
	v_mul_f32_e32 v87, v100, v87
	v_mul_f32_e32 v57, v101, v57
	v_mul_f32_e32 v92, v102, v92
	v_mul_f32_e32 v58, v103, v58
	v_mul_f32_e32 v93, v108, v93
	v_mul_f32_e32 v51, v51, v59
	v_mul_f32_e32 v52, v52, v86
	v_mul_f32_e32 v53, v53, v56
	v_mul_f32_e32 v54, v54, v87
	v_mul_f32_e32 v55, v55, v57
	v_mul_f32_e32 v56, v48, v92
	v_mul_f32_e32 v57, v49, v58
	v_mul_f32_e32 v58, v50, v93
	v_cvt_pk_bf16_f32 v48, v52, v53
	v_cvt_pk_bf16_f32 v49, v54, v55
	v_cvt_pk_bf16_f32 v50, v56, v57
	v_cvt_pk_bf16_f32 v51, v58, v51
	global_store_dwordx4 v[62:63], v[48:51], off
	v_lshl_add_u64 v[54:55], v[114:115], 0, v[168:169]
	v_lshl_add_u64 v[52:53], v[112:113], 0, v[168:169]
	s_waitcnt vmcnt(13)
	v_mov_b32_e32 v48, v210
	v_mov_b32_e32 v49, v211
	v_mov_b32_e32 v50, v212
	v_mov_b32_e32 v51, v213
	v_lshlrev_b32_e32 v59, 16, v51
	v_and_b32_e32 v51, 0xffff0000, v51
	v_lshlrev_b32_e32 v56, 16, v48
	v_and_b32_e32 v48, 0xffff0000, v48
	v_lshlrev_b32_e32 v57, 16, v49
	v_and_b32_e32 v49, 0xffff0000, v49
	v_lshlrev_b32_e32 v58, 16, v50
	v_and_b32_e32 v50, 0xffff0000, v50
	v_mul_f32_e32 v93, 0xbfb8aa3b, v51
	v_mul_f32_e32 v60, 0xbfb8aa3b, v56
	v_mul_f32_e32 v61, 0xbfb8aa3b, v48
	v_mul_f32_e32 v62, 0xbfb8aa3b, v57
	v_mul_f32_e32 v63, 0xbfb8aa3b, v49
	v_mul_f32_e32 v86, 0xbfb8aa3b, v58
	v_mul_f32_e32 v87, 0xbfb8aa3b, v50
	v_mul_f32_e32 v92, 0xbfb8aa3b, v59
	v_exp_f32_e32 v93, v93
	v_exp_f32_e32 v60, v60
	v_exp_f32_e32 v61, v61
	v_exp_f32_e32 v62, v62
	v_exp_f32_e32 v63, v63
	v_exp_f32_e32 v86, v86
	v_exp_f32_e32 v87, v87
	v_exp_f32_e32 v92, v92
	v_add_f32_e32 v93, 1.0, v93
	v_add_f32_e32 v60, 1.0, v60
	v_add_f32_e32 v61, 1.0, v61
	v_add_f32_e32 v62, 1.0, v62
	v_add_f32_e32 v63, 1.0, v63
	v_add_f32_e32 v86, 1.0, v86
	v_add_f32_e32 v87, 1.0, v87
	v_add_f32_e32 v92, 1.0, v92
	v_rcp_f32_e32 v93, v93
	v_rcp_f32_e32 v60, v60
	v_rcp_f32_e32 v61, v61
	v_rcp_f32_e32 v62, v62
	v_rcp_f32_e32 v63, v63
	v_rcp_f32_e32 v86, v86
	v_rcp_f32_e32 v87, v87
	v_rcp_f32_e32 v92, v92
	v_mul_f32_e32 v51, v93, v51
	v_mul_f32_e32 v56, v60, v56
	v_mul_f32_e32 v48, v61, v48
	v_mul_f32_e32 v57, v62, v57
	v_mul_f32_e32 v49, v63, v49
	v_mul_f32_e32 v58, v86, v58
	v_mul_f32_e32 v50, v87, v50
	v_mul_f32_e32 v59, v92, v59
	v_mul_f32_e32 v43, v43, v51
	v_mul_f32_e32 v44, v44, v56
	v_mul_f32_e32 v45, v45, v48
	v_mul_f32_e32 v46, v46, v57
	v_mul_f32_e32 v47, v47, v49
	v_mul_f32_e32 v48, v40, v58
	v_mul_f32_e32 v49, v41, v50
	v_mul_f32_e32 v50, v42, v59
	v_cvt_pk_bf16_f32 v40, v44, v45
	v_cvt_pk_bf16_f32 v41, v46, v47
	v_cvt_pk_bf16_f32 v42, v48, v49
	v_cvt_pk_bf16_f32 v43, v50, v43
	global_store_dwordx4 v[54:55], v[40:43], off
	v_lshl_add_u64 v[46:47], v[106:107], 0, v[168:169]
	v_lshl_add_u64 v[44:45], v[104:105], 0, v[168:169]
	s_waitcnt vmcnt(12)
; __device__ __forceinline__ float bflo(unsigned w) { return __uint_as_float(w << 16); }
; __device__ __forceinline__ float bfhi(unsigned w) { return __uint_as_float(w & 0xffff0000u); }
; __device__ __forceinline__ unsigned pk2(float lo, float hi) { unsigned r; asm("v_cvt_pk_bf16_f32 %0, %1, %2" : "=v"(r) : "v"(lo), "v"(hi)); return r; }
; __device__ __forceinline__ float siluf_(float x) { return x * __builtin_amdgcn_rcpf(1.0f + __expf(-x)); }
;     __device__ __forceinline__ void operator()(const f32x4 (&acc)[2][2][4][2], const Unit& u, int wr, int wc, int fr, int fq) const {
;         const int row0 = u.pm * BM + wr * 64 + fr, col0 = u.pn * BM + wc * 32 + 8 * fq;
; #pragma unroll
;         for (int bj = 0; bj < 2; ++bj) { const int col = col0 + bj * HALF;
;             const f32x4 b0 = *(const f32x4*)(bias + col), b1 = *(const f32x4*)(bias + col + 4), s0 = *(const f32x4*)(scale + col), s1 = *(const f32x4*)(scale + col + 4);
; #pragma unroll
;             for (int ai = 0; ai < 2; ++ai)
; #pragma unroll
;                 for (int m = 0; m < 4; ++m) { const int row = row0 + ai * HALF + m * 16;
;                     const u32x4 z = __builtin_nontemporal_load((const u32x4*)(proj + (size_t)row * NPROJ + C_ZP + col));
;                     f32x4 v0 = (acc[ai][bj][m][0] + b0) * s0, v1 = (acc[ai][bj][m][1] + b1) * s1;
;                     v0[0] *= siluf_(bflo(z.x)); v0[1] *= siluf_(bfhi(z.x)); v0[2] *= siluf_(bflo(z.y)); v0[3] *= siluf_(bfhi(z.y));
;                     v1[0] *= siluf_(bflo(z.z)); v1[1] *= siluf_(bfhi(z.z)); v1[2] *= siluf_(bflo(z.w)); v1[3] *= siluf_(bfhi(z.w));
;                     u32x4 w; w.x = pk2(v0[0], v0[1]); w.y = pk2(v0[2], v0[3]); w.z = pk2(v1[0], v1[1]); w.w = pk2(v1[2], v1[3]);
;                     *(u32x4*)(a2 + (size_t)row * 4096 + 2048 + col) = w; } }
;     }
	v_mov_b32_e32 v40, v214
	v_mov_b32_e32 v41, v215
	v_mov_b32_e32 v42, v216
	v_mov_b32_e32 v43, v217
	v_lshlrev_b32_e32 v51, 16, v43
	v_and_b32_e32 v43, 0xffff0000, v43
	v_lshlrev_b32_e32 v48, 16, v40
	v_and_b32_e32 v40, 0xffff0000, v40
	v_lshlrev_b32_e32 v49, 16, v41
	v_and_b32_e32 v41, 0xffff0000, v41
	v_lshlrev_b32_e32 v50, 16, v42
	v_and_b32_e32 v42, 0xffff0000, v42
	v_mul_f32_e32 v59, 0xbfb8aa3b, v43
	v_mul_f32_e32 v52, 0xbfb8aa3b, v48
	v_mul_f32_e32 v53, 0xbfb8aa3b, v40
	v_mul_f32_e32 v54, 0xbfb8aa3b, v49
	v_mul_f32_e32 v55, 0xbfb8aa3b, v41
	v_mul_f32_e32 v56, 0xbfb8aa3b, v50
	v_mul_f32_e32 v57, 0xbfb8aa3b, v42
	v_mul_f32_e32 v58, 0xbfb8aa3b, v51
	v_exp_f32_e32 v59, v59
	v_exp_f32_e32 v52, v52
	v_exp_f32_e32 v53, v53
	v_exp_f32_e32 v54, v54
	v_exp_f32_e32 v55, v55
	v_exp_f32_e32 v56, v56
	v_exp_f32_e32 v57, v57
	v_exp_f32_e32 v58, v58
	v_add_f32_e32 v59, 1.0, v59
	v_add_f32_e32 v52, 1.0, v52
	v_add_f32_e32 v53, 1.0, v53
	v_add_f32_e32 v54, 1.0, v54
	v_add_f32_e32 v55, 1.0, v55
	v_add_f32_e32 v56, 1.0, v56
	v_add_f32_e32 v57, 1.0, v57
	v_add_f32_e32 v58, 1.0, v58
	v_rcp_f32_e32 v59, v59
	v_rcp_f32_e32 v52, v52
	v_rcp_f32_e32 v53, v53
	v_rcp_f32_e32 v54, v54
	v_rcp_f32_e32 v55, v55
	v_rcp_f32_e32 v56, v56
	v_rcp_f32_e32 v57, v57
	v_rcp_f32_e32 v58, v58
	v_mul_f32_e32 v43, v59, v43
	v_mul_f32_e32 v48, v52, v48
	v_mul_f32_e32 v40, v53, v40
	v_mul_f32_e32 v49, v54, v49
	v_mul_f32_e32 v41, v55, v41
	v_mul_f32_e32 v50, v56, v50
	v_mul_f32_e32 v42, v57, v42
	v_mul_f32_e32 v51, v58, v51
	v_mul_f32_e32 v35, v35, v43
	v_mul_f32_e32 v36, v36, v48
	v_mul_f32_e32 v37, v37, v40
	v_mul_f32_e32 v38, v38, v49
	v_mul_f32_e32 v39, v39, v41
	v_mul_f32_e32 v40, v32, v50
	v_mul_f32_e32 v41, v33, v42
	v_mul_f32_e32 v42, v34, v51
	v_cvt_pk_bf16_f32 v32, v36, v37
	v_cvt_pk_bf16_f32 v33, v38, v39
	v_cvt_pk_bf16_f32 v34, v40, v41
	v_cvt_pk_bf16_f32 v35, v42, v35
	global_store_dwordx4 v[46:47], v[32:35], off
	v_lshl_add_u64 v[38:39], v[98:99], 0, v[168:169]
	v_lshl_add_u64 v[36:37], v[96:97], 0, v[168:169]
	s_waitcnt vmcnt(11)
	v_mov_b32_e32 v32, v218
	v_mov_b32_e32 v33, v219
	v_mov_b32_e32 v34, v220
	v_mov_b32_e32 v35, v221
	v_lshlrev_b32_e32 v43, 16, v35
	v_and_b32_e32 v35, 0xffff0000, v35
	v_lshlrev_b32_e32 v40, 16, v32
	v_and_b32_e32 v32, 0xffff0000, v32
	v_lshlrev_b32_e32 v41, 16, v33
	v_and_b32_e32 v33, 0xffff0000, v33
	v_lshlrev_b32_e32 v42, 16, v34
	v_and_b32_e32 v34, 0xffff0000, v34
	v_mul_f32_e32 v51, 0xbfb8aa3b, v35
	v_mul_f32_e32 v44, 0xbfb8aa3b, v40
	v_mul_f32_e32 v45, 0xbfb8aa3b, v32
	v_mul_f32_e32 v46, 0xbfb8aa3b, v41
	v_mul_f32_e32 v47, 0xbfb8aa3b, v33
	v_mul_f32_e32 v48, 0xbfb8aa3b, v42
	v_mul_f32_e32 v49, 0xbfb8aa3b, v34
	v_mul_f32_e32 v50, 0xbfb8aa3b, v43
	v_exp_f32_e32 v51, v51
	v_exp_f32_e32 v44, v44
	v_exp_f32_e32 v45, v45
	v_exp_f32_e32 v46, v46
	v_exp_f32_e32 v47, v47
	v_exp_f32_e32 v48, v48
	v_exp_f32_e32 v49, v49
	v_exp_f32_e32 v50, v50
	v_add_f32_e32 v51, 1.0, v51
	v_add_f32_e32 v44, 1.0, v44
	v_add_f32_e32 v45, 1.0, v45
	v_add_f32_e32 v46, 1.0, v46
	v_add_f32_e32 v47, 1.0, v47
	v_add_f32_e32 v48, 1.0, v48
	v_add_f32_e32 v49, 1.0, v49
	v_add_f32_e32 v50, 1.0, v50
	v_rcp_f32_e32 v51, v51
	v_rcp_f32_e32 v44, v44
	v_rcp_f32_e32 v45, v45
	v_rcp_f32_e32 v46, v46
	v_rcp_f32_e32 v47, v47
	v_rcp_f32_e32 v48, v48
	v_rcp_f32_e32 v49, v49
	v_rcp_f32_e32 v50, v50
	v_mul_f32_e32 v35, v51, v35
	v_mul_f32_e32 v40, v44, v40
	v_mul_f32_e32 v32, v45, v32
	v_mul_f32_e32 v41, v46, v41
	v_mul_f32_e32 v33, v47, v33
	v_mul_f32_e32 v42, v48, v42
	v_mul_f32_e32 v34, v49, v34
	v_mul_f32_e32 v43, v50, v43
	v_mul_f32_e32 v27, v27, v35
	v_mul_f32_e32 v28, v28, v40
	v_mul_f32_e32 v29, v29, v32
	v_mul_f32_e32 v30, v30, v41
	v_mul_f32_e32 v31, v31, v33
	v_mul_f32_e32 v32, v24, v42
	v_mul_f32_e32 v33, v25, v34
	v_mul_f32_e32 v34, v26, v43
	v_cvt_pk_bf16_f32 v24, v28, v29
	v_cvt_pk_bf16_f32 v25, v30, v31
	v_cvt_pk_bf16_f32 v26, v32, v33
	v_cvt_pk_bf16_f32 v27, v34, v27
	global_store_dwordx4 v[38:39], v[24:27], off
	v_lshl_add_u64 v[30:31], v[90:91], 0, v[168:169]
	v_lshl_add_u64 v[28:29], v[88:89], 0, v[168:169]
	s_waitcnt vmcnt(10)
; __device__ __forceinline__ float bflo(unsigned w) { return __uint_as_float(w << 16); }
; __device__ __forceinline__ float bfhi(unsigned w) { return __uint_as_float(w & 0xffff0000u); }
; __device__ __forceinline__ unsigned pk2(float lo, float hi) { unsigned r; asm("v_cvt_pk_bf16_f32 %0, %1, %2" : "=v"(r) : "v"(lo), "v"(hi)); return r; }
; __device__ __forceinline__ float siluf_(float x) { return x * __builtin_amdgcn_rcpf(1.0f + __expf(-x)); }
; #define PG8_WAIT_V(n) asm volatile("s_waitcnt vmcnt(" #n ")" ::: "memory")
; #define PG8_BAR __builtin_amdgcn_s_barrier()
; template <class Epi>
; __device__ __forceinline__ void gemm_phase(LAS unsigned char* lds, const GemmD g, const Epi& E) {
;     ...
;     PG8_WAIT_V(0);
;     if (wr == 0) PG8_BAR;
;     PG8_BAR;
;     __device__ __forceinline__ void operator()(const f32x4 (&acc)[2][2][4][2], const Unit& u, int wr, int wc, int fr, int fq) const {
;         const int row0 = u.pm * BM + wr * 64 + fr, col0 = u.pn * BM + wc * 32 + 8 * fq;
; #pragma unroll
;         for (int bj = 0; bj < 2; ++bj) { const int col = col0 + bj * HALF;
;             const f32x4 b0 = *(const f32x4*)(bias + col), b1 = *(const f32x4*)(bias + col + 4), s0 = *(const f32x4*)(scale + col), s1 = *(const f32x4*)(scale + col + 4);
; #pragma unroll
;             for (int ai = 0; ai < 2; ++ai)
; #pragma unroll
;                 for (int m = 0; m < 4; ++m) { const int row = row0 + ai * HALF + m * 16;
;                     const u32x4 z = __builtin_nontemporal_load((const u32x4*)(proj + (size_t)row * NPROJ + C_ZP + col));
;                     f32x4 v0 = (acc[ai][bj][m][0] + b0) * s0, v1 = (acc[ai][bj][m][1] + b1) * s1;
;                     v0[0] *= siluf_(bflo(z.x)); v0[1] *= siluf_(bfhi(z.x)); v0[2] *= siluf_(bflo(z.y)); v0[3] *= siluf_(bfhi(z.y));
;                     v1[0] *= siluf_(bflo(z.z)); v1[1] *= siluf_(bfhi(z.z)); v1[2] *= siluf_(bflo(z.w)); v1[3] *= siluf_(bfhi(z.w));
;                     u32x4 w; w.x = pk2(v0[0], v0[1]); w.y = pk2(v0[2], v0[3]); w.z = pk2(v1[0], v1[1]); w.w = pk2(v1[2], v1[3]);
;                     *(u32x4*)(a2 + (size_t)row * 4096 + 2048 + col) = w; } }
;     }
	v_mov_b32_e32 v24, v222
	v_mov_b32_e32 v25, v223
	v_mov_b32_e32 v26, v224
	v_mov_b32_e32 v27, v225
	v_lshlrev_b32_e32 v35, 16, v27
	v_and_b32_e32 v27, 0xffff0000, v27
	v_lshlrev_b32_e32 v32, 16, v24
	v_and_b32_e32 v24, 0xffff0000, v24
	v_lshlrev_b32_e32 v33, 16, v25
	v_and_b32_e32 v25, 0xffff0000, v25
	v_lshlrev_b32_e32 v34, 16, v26
	v_and_b32_e32 v26, 0xffff0000, v26
	v_mul_f32_e32 v43, 0xbfb8aa3b, v27
	v_mul_f32_e32 v36, 0xbfb8aa3b, v32
	v_mul_f32_e32 v37, 0xbfb8aa3b, v24
	v_mul_f32_e32 v38, 0xbfb8aa3b, v33
	v_mul_f32_e32 v39, 0xbfb8aa3b, v25
	v_mul_f32_e32 v40, 0xbfb8aa3b, v34
	v_mul_f32_e32 v41, 0xbfb8aa3b, v26
	v_mul_f32_e32 v42, 0xbfb8aa3b, v35
	v_exp_f32_e32 v43, v43
	v_exp_f32_e32 v36, v36
	v_exp_f32_e32 v37, v37
	v_exp_f32_e32 v38, v38
	v_exp_f32_e32 v39, v39
	v_exp_f32_e32 v40, v40
	v_exp_f32_e32 v41, v41
	v_exp_f32_e32 v42, v42
	v_add_f32_e32 v43, 1.0, v43
	v_add_f32_e32 v36, 1.0, v36
	v_add_f32_e32 v37, 1.0, v37
	v_add_f32_e32 v38, 1.0, v38
	v_add_f32_e32 v39, 1.0, v39
	v_add_f32_e32 v40, 1.0, v40
	v_add_f32_e32 v41, 1.0, v41
	v_add_f32_e32 v42, 1.0, v42
	v_rcp_f32_e32 v43, v43
	v_rcp_f32_e32 v36, v36
	v_rcp_f32_e32 v37, v37
	v_rcp_f32_e32 v38, v38
	v_rcp_f32_e32 v39, v39
	v_rcp_f32_e32 v40, v40
	v_rcp_f32_e32 v41, v41
	v_rcp_f32_e32 v42, v42
	v_mul_f32_e32 v27, v43, v27
	v_mul_f32_e32 v32, v36, v32
	v_mul_f32_e32 v24, v37, v24
	v_mul_f32_e32 v33, v38, v33
	v_mul_f32_e32 v25, v39, v25
	v_mul_f32_e32 v34, v40, v34
	v_mul_f32_e32 v26, v41, v26
	v_mul_f32_e32 v35, v42, v35
	v_mul_f32_e32 v19, v19, v27
	v_mul_f32_e32 v20, v20, v32
	v_mul_f32_e32 v21, v21, v24
	v_mul_f32_e32 v22, v22, v33
	v_mul_f32_e32 v23, v23, v25
	v_mul_f32_e32 v24, v16, v34
	v_mul_f32_e32 v25, v17, v26
	v_mul_f32_e32 v26, v18, v35
	v_cvt_pk_bf16_f32 v16, v20, v21
	v_cvt_pk_bf16_f32 v17, v22, v23
	v_cvt_pk_bf16_f32 v18, v24, v25
	v_cvt_pk_bf16_f32 v19, v26, v19
	global_store_dwordx4 v[30:31], v[16:19], off
	v_lshl_add_u64 v[22:23], v[84:85], 0, v[168:169]
	v_lshl_add_u64 v[20:21], v[82:83], 0, v[168:169]
	s_waitcnt vmcnt(9)
	v_mov_b32_e32 v16, v226
	v_mov_b32_e32 v17, v227
	v_mov_b32_e32 v18, v228
	v_mov_b32_e32 v19, v229
	v_lshlrev_b32_e32 v27, 16, v19
	v_and_b32_e32 v19, 0xffff0000, v19
	v_lshlrev_b32_e32 v24, 16, v16
	v_and_b32_e32 v16, 0xffff0000, v16
	v_lshlrev_b32_e32 v25, 16, v17
	v_and_b32_e32 v17, 0xffff0000, v17
	v_lshlrev_b32_e32 v26, 16, v18
	v_and_b32_e32 v18, 0xffff0000, v18
	v_mul_f32_e32 v35, 0xbfb8aa3b, v19
	v_mul_f32_e32 v28, 0xbfb8aa3b, v24
	v_mul_f32_e32 v29, 0xbfb8aa3b, v16
	v_mul_f32_e32 v30, 0xbfb8aa3b, v25
	v_mul_f32_e32 v31, 0xbfb8aa3b, v17
	v_mul_f32_e32 v32, 0xbfb8aa3b, v26
	v_mul_f32_e32 v33, 0xbfb8aa3b, v18
	v_mul_f32_e32 v34, 0xbfb8aa3b, v27
	v_exp_f32_e32 v35, v35
	v_exp_f32_e32 v28, v28
	v_exp_f32_e32 v29, v29
	v_exp_f32_e32 v30, v30
	v_exp_f32_e32 v31, v31
	v_exp_f32_e32 v32, v32
	v_exp_f32_e32 v33, v33
	v_exp_f32_e32 v34, v34
	v_add_f32_e32 v35, 1.0, v35
	v_add_f32_e32 v28, 1.0, v28
	v_add_f32_e32 v29, 1.0, v29
	v_add_f32_e32 v30, 1.0, v30
	v_add_f32_e32 v31, 1.0, v31
	v_add_f32_e32 v32, 1.0, v32
	v_add_f32_e32 v33, 1.0, v33
	v_add_f32_e32 v34, 1.0, v34
	v_rcp_f32_e32 v35, v35
	v_rcp_f32_e32 v28, v28
	v_rcp_f32_e32 v29, v29
	v_rcp_f32_e32 v30, v30
	v_rcp_f32_e32 v31, v31
	v_rcp_f32_e32 v32, v32
	v_rcp_f32_e32 v33, v33
	v_rcp_f32_e32 v34, v34
	v_mul_f32_e32 v19, v35, v19
	v_mul_f32_e32 v24, v28, v24
	v_mul_f32_e32 v16, v29, v16
	v_mul_f32_e32 v25, v30, v25
	v_mul_f32_e32 v17, v31, v17
	v_mul_f32_e32 v26, v32, v26
	v_mul_f32_e32 v18, v33, v18
	v_mul_f32_e32 v27, v34, v27
	v_mul_f32_e32 v11, v11, v19
	v_mul_f32_e32 v12, v12, v24
	v_mul_f32_e32 v13, v13, v16
	v_mul_f32_e32 v14, v14, v25
	v_mul_f32_e32 v15, v15, v17
	v_mul_f32_e32 v16, v8, v26
	v_mul_f32_e32 v17, v9, v18
	v_mul_f32_e32 v18, v10, v27
	v_cvt_pk_bf16_f32 v8, v12, v13
	v_cvt_pk_bf16_f32 v9, v14, v15
	v_cvt_pk_bf16_f32 v10, v16, v17
	v_cvt_pk_bf16_f32 v11, v18, v11
	global_store_dwordx4 v[22:23], v[8:11], off
	v_lshl_add_u64 v[12:13], v[80:81], 0, v[168:169]
	s_waitcnt vmcnt(8)
	v_mov_b32_e32 v8, v230
	v_mov_b32_e32 v9, v231
	v_mov_b32_e32 v10, v232
	v_mov_b32_e32 v11, v233
	v_lshlrev_b32_e32 v17, 16, v11
	v_and_b32_e32 v11, 0xffff0000, v11
	v_lshlrev_b32_e32 v14, 16, v8
	v_and_b32_e32 v8, 0xffff0000, v8
	v_lshlrev_b32_e32 v15, 16, v9
	v_and_b32_e32 v9, 0xffff0000, v9
	v_lshlrev_b32_e32 v16, 16, v10
	v_and_b32_e32 v10, 0xffff0000, v10
	v_mul_f32_e32 v25, 0xbfb8aa3b, v11
	v_mul_f32_e32 v18, 0xbfb8aa3b, v14
	v_mul_f32_e32 v19, 0xbfb8aa3b, v8
	v_mul_f32_e32 v20, 0xbfb8aa3b, v15
	v_mul_f32_e32 v21, 0xbfb8aa3b, v9
	v_mul_f32_e32 v22, 0xbfb8aa3b, v16
	v_mul_f32_e32 v23, 0xbfb8aa3b, v10
	v_mul_f32_e32 v24, 0xbfb8aa3b, v17
	v_exp_f32_e32 v25, v25
	v_exp_f32_e32 v18, v18
	v_exp_f32_e32 v19, v19
	v_exp_f32_e32 v20, v20
	v_exp_f32_e32 v21, v21
	v_exp_f32_e32 v22, v22
	v_exp_f32_e32 v23, v23
	v_exp_f32_e32 v24, v24
	v_add_f32_e32 v25, 1.0, v25
	v_add_f32_e32 v18, 1.0, v18
	v_add_f32_e32 v19, 1.0, v19
	v_add_f32_e32 v20, 1.0, v20
	v_add_f32_e32 v21, 1.0, v21
	v_add_f32_e32 v22, 1.0, v22
	v_add_f32_e32 v23, 1.0, v23
	v_add_f32_e32 v24, 1.0, v24
	v_rcp_f32_e32 v25, v25
	v_rcp_f32_e32 v18, v18
	v_rcp_f32_e32 v19, v19
	v_rcp_f32_e32 v20, v20
	v_rcp_f32_e32 v21, v21
	v_rcp_f32_e32 v22, v22
	v_rcp_f32_e32 v23, v23
	v_rcp_f32_e32 v24, v24
	v_mul_f32_e32 v11, v25, v11
	v_mul_f32_e32 v14, v18, v14
	v_mul_f32_e32 v8, v19, v8
	v_mul_f32_e32 v15, v20, v15
	v_mul_f32_e32 v9, v21, v9
	v_mul_f32_e32 v16, v22, v16
	v_mul_f32_e32 v10, v23, v10
	v_mul_f32_e32 v17, v24, v17
	v_mul_f32_e32 v3, v3, v11
	v_mul_f32_e32 v4, v4, v14
	v_mul_f32_e32 v5, v5, v8
	v_mul_f32_e32 v6, v6, v15
	v_mul_f32_e32 v7, v7, v9
	v_mul_f32_e32 v8, v0, v16
	v_mul_f32_e32 v9, v1, v10
	v_mul_f32_e32 v10, v2, v17
	v_cvt_pk_bf16_f32 v0, v4, v5
	v_cvt_pk_bf16_f32 v1, v6, v7
	v_cvt_pk_bf16_f32 v2, v8, v9
	v_cvt_pk_bf16_f32 v3, v10, v3
	global_store_dwordx4 v[12:13], v[0:3], off
	s_cbranch_vccz .LBB0_595
	s_waitcnt vmcnt(0)
	s_cmpk_gt_u32 s33, 0xff
	s_cbranch_scc1 .LBB0_604
	s_barrier

; template <class Epi>
; __device__ __forceinline__ void gemm_phase(LAS unsigned char* lds, const GemmD g, const Epi& E) {
;     ...
;         for (int t = 0; t < nt; t += 2) PG8_KITER(t);
.LBB0_697:
	s_add_u32 s34, vcc_lo, 0xfff80080
	s_addc_u32 s35, vcc_hi, -1
	s_add_i32 s84, 0, 0x10000
	v_add_u32_e32 v0, s84, v155
	ds_read_b128 v[146:149], v0
	ds_read_b128 v[150:153], v0 offset:1024
	ds_read_b128 v[158:161], v0 offset:2048
	ds_read_b128 v[162:165], v0 offset:3072
	s_cmp_eq_u32 s95, 28
	s_cselect_b32 s57, s1, s35
	s_cselect_b32 s56, s36, s34
	s_cselect_b32 s35, s31, s66
	s_cselect_b32 s34, s37, s51
	v_lshl_add_u64 v[170:171], vcc, 0, v[142:143]
	s_add_i32 m0, s2, 0xc000
	ds_read_b128 v[166:169], v157
	ds_read_b128 v[180:183], v157 offset:1024
	ds_read_b128 v[184:187], v157 offset:2048
	ds_read_b128 v[188:191], v157 offset:3072
	ds_read_b128 v[204:207], v157 offset:4096
	ds_read_b128 v[208:211], v157 offset:5120
	ds_read_b128 v[212:215], v157 offset:6144
	ds_read_b128 v[216:219], v157 offset:7168
	global_load_lds_dwordx4 v[170:171], off
	v_lshl_add_u64 v[170:171], vcc, 0, v[144:145]
	s_add_i32 m0, s2, 0xe000
	s_nop 0
	global_load_lds_dwordx4 v[170:171], off
	s_waitcnt lgkmcnt(8)
	s_barrier
	s_waitcnt lgkmcnt(0)
	s_setprio 1
	s_waitcnt lgkmcnt(0)
	v_mfma_f32_16x16x32_bf16 v[126:129], v[146:149], v[166:169], v[126:129]
	v_mfma_f32_16x16x32_bf16 v[122:125], v[158:161], v[166:169], v[122:125]
	v_mfma_f32_16x16x32_bf16 v[110:113], v[146:149], v[184:187], v[110:113]
	v_mfma_f32_16x16x32_bf16 v[106:109], v[158:161], v[184:187], v[106:109]
	v_mfma_f32_16x16x32_bf16 v[94:97], v[146:149], v[204:207], v[94:97]
	v_mfma_f32_16x16x32_bf16 v[90:93], v[158:161], v[204:207], v[90:93]
	v_mfma_f32_16x16x32_bf16 v[78:81], v[146:149], v[212:215], v[78:81]
	v_mfma_f32_16x16x32_bf16 v[74:77], v[158:161], v[212:215], v[74:77]
	v_mfma_f32_16x16x32_bf16 v[126:129], v[150:153], v[180:183], v[126:129]
	v_mfma_f32_16x16x32_bf16 v[122:125], v[162:165], v[180:183], v[122:125]
	v_mfma_f32_16x16x32_bf16 v[110:113], v[150:153], v[188:191], v[110:113]
	v_mfma_f32_16x16x32_bf16 v[106:109], v[162:165], v[188:191], v[106:109]
	v_mfma_f32_16x16x32_bf16 v[94:97], v[150:153], v[208:211], v[94:97]
	v_mfma_f32_16x16x32_bf16 v[90:93], v[162:165], v[208:211], v[90:93]
	v_mfma_f32_16x16x32_bf16 v[78:81], v[150:153], v[216:219], v[78:81]
	v_mfma_f32_16x16x32_bf16 v[74:77], v[162:165], v[216:219], v[74:77]
	s_setprio 0
	s_barrier
	s_add_i32 s86, 0, 0x14000
	s_add_i32 s84, s84, s97
	v_add_u32_e32 v0, s86, v155
	v_lshl_add_u64 v[170:171], s[34:35], 0, v[132:133]
	s_mov_b32 m0, s84
	ds_read_b128 v[220:223], v0
	ds_read_b128 v[224:227], v0 offset:1024
	ds_read_b128 v[228:231], v0 offset:2048
	ds_read_b128 v[232:235], v0 offset:3072
	global_load_lds_dwordx4 v[170:171], off
	v_lshl_add_u64 v[236:237], s[34:35], 0, v[136:137]
	s_add_i32 m0, s84, 0x2000
	s_nop 0
	global_load_lds_dwordx4 v[236:237], off
	s_barrier
	s_waitcnt lgkmcnt(0)
	s_setprio 1
	s_waitcnt lgkmcnt(0)
	v_mfma_f32_16x16x32_bf16 v[118:121], v[220:223], v[166:169], v[118:121]
	v_mfma_f32_16x16x32_bf16 v[114:117], v[228:231], v[166:169], v[114:117]
	v_mfma_f32_16x16x32_bf16 v[102:105], v[220:223], v[184:187], v[102:105]
	v_mfma_f32_16x16x32_bf16 v[98:101], v[228:231], v[184:187], v[98:101]
	v_mfma_f32_16x16x32_bf16 v[86:89], v[220:223], v[204:207], v[86:89]
	v_mfma_f32_16x16x32_bf16 v[82:85], v[228:231], v[204:207], v[82:85]
	v_mfma_f32_16x16x32_bf16 v[70:73], v[220:223], v[212:215], v[70:73]
	v_mfma_f32_16x16x32_bf16 v[66:69], v[228:231], v[212:215], v[66:69]
	v_mfma_f32_16x16x32_bf16 v[118:121], v[224:227], v[180:183], v[118:121]
	v_mfma_f32_16x16x32_bf16 v[114:117], v[232:235], v[180:183], v[114:117]
	v_mfma_f32_16x16x32_bf16 v[102:105], v[224:227], v[188:191], v[102:105]
	v_mfma_f32_16x16x32_bf16 v[98:101], v[232:235], v[188:191], v[98:101]
	v_mfma_f32_16x16x32_bf16 v[86:89], v[224:227], v[208:211], v[86:89]
	v_mfma_f32_16x16x32_bf16 v[82:85], v[232:235], v[208:211], v[82:85]
	v_mfma_f32_16x16x32_bf16 v[70:73], v[224:227], v[216:219], v[70:73]
	v_mfma_f32_16x16x32_bf16 v[66:69], v[232:235], v[216:219], v[66:69]
	s_setprio 0
	s_barrier
	s_mov_b32 m0, s2
	v_lshl_add_u64 v[238:239], s[56:57], 0, v[130:131]
	ds_read_b128 v[166:169], v157 offset:16384
	ds_read_b128 v[180:183], v157 offset:17408
	ds_read_b128 v[184:187], v157 offset:18432
	ds_read_b128 v[188:191], v157 offset:19456
	ds_read_b128 v[204:207], v157 offset:20480
	ds_read_b128 v[208:211], v157 offset:21504
	ds_read_b128 v[212:215], v157 offset:22528
	ds_read_b128 v[216:219], v157 offset:23552
	global_load_lds_dwordx4 v[238:239], off
	v_lshl_add_u64 v[240:241], s[56:57], 0, v[134:135]
	s_mov_b32 m0, s3
	s_nop 0
	global_load_lds_dwordx4 v[240:241], off
	s_barrier
	s_waitcnt lgkmcnt(0)
	s_setprio 1
	s_waitcnt lgkmcnt(0)
	v_mfma_f32_16x16x32_bf16 v[62:65], v[146:149], v[166:169], v[62:65]
	v_mfma_f32_16x16x32_bf16 v[58:61], v[158:161], v[166:169], v[58:61]
	v_mfma_f32_16x16x32_bf16 v[46:49], v[146:149], v[184:187], v[46:49]
	v_mfma_f32_16x16x32_bf16 v[42:45], v[158:161], v[184:187], v[42:45]
	v_mfma_f32_16x16x32_bf16 v[30:33], v[146:149], v[204:207], v[30:33]
	v_mfma_f32_16x16x32_bf16 v[26:29], v[158:161], v[204:207], v[26:29]
	v_mfma_f32_16x16x32_bf16 v[14:17], v[146:149], v[212:215], v[14:17]
	v_mfma_f32_16x16x32_bf16 v[10:13], v[158:161], v[212:215], v[10:13]
	v_mfma_f32_16x16x32_bf16 v[62:65], v[150:153], v[180:183], v[62:65]
	v_mfma_f32_16x16x32_bf16 v[58:61], v[162:165], v[180:183], v[58:61]
	v_mfma_f32_16x16x32_bf16 v[46:49], v[150:153], v[188:191], v[46:49]
	v_mfma_f32_16x16x32_bf16 v[42:45], v[162:165], v[188:191], v[42:45]
	v_mfma_f32_16x16x32_bf16 v[30:33], v[150:153], v[208:211], v[30:33]
	v_mfma_f32_16x16x32_bf16 v[26:29], v[162:165], v[208:211], v[26:29]
	v_mfma_f32_16x16x32_bf16 v[14:17], v[150:153], v[216:219], v[14:17]
	v_mfma_f32_16x16x32_bf16 v[10:13], v[162:165], v[216:219], v[10:13]
	s_setprio 0
	s_barrier
; template <class Epi>
; __device__ __forceinline__ void gemm_phase(LAS unsigned char* lds, const GemmD g, const Epi& E) {
;     ...
;         for (int t = 0; t < nt; t += 2) PG8_KITER(t);
	s_add_u32 s84, s34, 0x80000
	s_addc_u32 s85, s35, 0
	s_add_i32 s86, s86, s97
	v_lshl_add_u64 v[146:147], s[84:85], 0, v[132:133]
	s_mov_b32 m0, s86
	s_nop 0
	global_load_lds_dwordx4 v[146:147], off
	v_lshl_add_u64 v[146:147], s[84:85], 0, v[136:137]
	s_add_i32 m0, s86, 0x2000
	s_nop 0
	global_load_lds_dwordx4 v[146:147], off
	s_waitcnt vmcnt(6)
	s_barrier
	s_setprio 1
	v_mfma_f32_16x16x32_bf16 v[54:57], v[220:223], v[166:169], v[54:57]
	v_mfma_f32_16x16x32_bf16 v[50:53], v[228:231], v[166:169], v[50:53]
	v_mfma_f32_16x16x32_bf16 v[38:41], v[220:223], v[184:187], v[38:41]
	v_mfma_f32_16x16x32_bf16 v[34:37], v[228:231], v[184:187], v[34:37]
	v_mfma_f32_16x16x32_bf16 v[22:25], v[220:223], v[204:207], v[22:25]
	v_mfma_f32_16x16x32_bf16 v[18:21], v[228:231], v[204:207], v[18:21]
	v_mfma_f32_16x16x32_bf16 v[6:9], v[220:223], v[212:215], v[6:9]
	v_mfma_f32_16x16x32_bf16 v[2:5], v[228:231], v[212:215], v[2:5]
	v_mfma_f32_16x16x32_bf16 v[54:57], v[224:227], v[180:183], v[54:57]
	v_mfma_f32_16x16x32_bf16 v[50:53], v[232:235], v[180:183], v[50:53]
	v_mfma_f32_16x16x32_bf16 v[38:41], v[224:227], v[188:191], v[38:41]
	v_mfma_f32_16x16x32_bf16 v[34:37], v[232:235], v[188:191], v[34:37]
	v_mfma_f32_16x16x32_bf16 v[22:25], v[224:227], v[208:211], v[22:25]
	v_mfma_f32_16x16x32_bf16 v[18:21], v[232:235], v[208:211], v[18:21]
	v_mfma_f32_16x16x32_bf16 v[6:9], v[224:227], v[216:219], v[6:9]
	v_mfma_f32_16x16x32_bf16 v[2:5], v[232:235], v[216:219], v[2:5]
	s_setprio 0
	s_barrier
	s_add_i32 s84, 0, 0x18000
	v_add_u32_e32 v0, s84, v155
	ds_read_b128 v[146:149], v0
	ds_read_b128 v[150:153], v0 offset:1024
	ds_read_b128 v[158:161], v0 offset:2048
	ds_read_b128 v[162:165], v0 offset:3072
	s_add_u32 s56, s56, 0x80000
	s_addc_u32 s57, s57, 0
	s_mov_b32 m0, s83
	v_lshl_add_u64 v[220:221], s[56:57], 0, v[130:131]
	ds_read_b128 v[166:169], v157 offset:32768
	ds_read_b128 v[180:183], v157 offset:33792
	ds_read_b128 v[184:187], v157 offset:34816
	ds_read_b128 v[188:191], v157 offset:35840
	ds_read_b128 v[204:207], v157 offset:36864
	ds_read_b128 v[208:211], v157 offset:37888
	ds_read_b128 v[212:215], v157 offset:38912
	ds_read_b128 v[216:219], v157 offset:39936
	global_load_lds_dwordx4 v[220:221], off
	v_lshl_add_u64 v[220:221], s[56:57], 0, v[134:135]
	s_mov_b32 m0, s70
	s_nop 0
	global_load_lds_dwordx4 v[220:221], off
	s_waitcnt lgkmcnt(8)
	s_barrier
	s_waitcnt lgkmcnt(0)
	s_setprio 1
	s_waitcnt lgkmcnt(0)
	v_mfma_f32_16x16x32_bf16 v[126:129], v[146:149], v[166:169], v[126:129]
	v_mfma_f32_16x16x32_bf16 v[122:125], v[158:161], v[166:169], v[122:125]
	v_mfma_f32_16x16x32_bf16 v[110:113], v[146:149], v[184:187], v[110:113]
	v_mfma_f32_16x16x32_bf16 v[106:109], v[158:161], v[184:187], v[106:109]
	v_mfma_f32_16x16x32_bf16 v[94:97], v[146:149], v[204:207], v[94:97]
	v_mfma_f32_16x16x32_bf16 v[90:93], v[158:161], v[204:207], v[90:93]
	v_mfma_f32_16x16x32_bf16 v[78:81], v[146:149], v[212:215], v[78:81]
	v_mfma_f32_16x16x32_bf16 v[74:77], v[158:161], v[212:215], v[74:77]
	v_mfma_f32_16x16x32_bf16 v[126:129], v[150:153], v[180:183], v[126:129]
	v_mfma_f32_16x16x32_bf16 v[122:125], v[162:165], v[180:183], v[122:125]
	v_mfma_f32_16x16x32_bf16 v[110:113], v[150:153], v[188:191], v[110:113]
	v_mfma_f32_16x16x32_bf16 v[106:109], v[162:165], v[188:191], v[106:109]
	v_mfma_f32_16x16x32_bf16 v[94:97], v[150:153], v[208:211], v[94:97]
	v_mfma_f32_16x16x32_bf16 v[90:93], v[162:165], v[208:211], v[90:93]
	v_mfma_f32_16x16x32_bf16 v[78:81], v[150:153], v[216:219], v[78:81]
	v_mfma_f32_16x16x32_bf16 v[74:77], v[162:165], v[216:219], v[74:77]
	s_setprio 0
	s_barrier
	s_add_i32 s56, 0, 0x1c000
	s_add_i32 s57, s84, s97
	v_add_u32_e32 v0, s56, v155
	v_lshl_add_u64 v[170:171], v[170:171], 0, s[48:49]
	s_mov_b32 m0, s57
	ds_read_b128 v[220:223], v0
	ds_read_b128 v[224:227], v0 offset:1024
	ds_read_b128 v[228:231], v0 offset:2048
	ds_read_b128 v[232:235], v0 offset:3072
	global_load_lds_dwordx4 v[170:171], off
	v_lshl_add_u64 v[170:171], v[236:237], 0, s[48:49]
	s_add_i32 m0, s57, 0x2000
	s_nop 0
	global_load_lds_dwordx4 v[170:171], off
	s_barrier
	s_waitcnt lgkmcnt(0)
	s_setprio 1
	s_waitcnt lgkmcnt(0)
	v_mfma_f32_16x16x32_bf16 v[118:121], v[220:223], v[166:169], v[118:121]
	v_mfma_f32_16x16x32_bf16 v[114:117], v[228:231], v[166:169], v[114:117]
	v_mfma_f32_16x16x32_bf16 v[102:105], v[220:223], v[184:187], v[102:105]
	v_mfma_f32_16x16x32_bf16 v[98:101], v[228:231], v[184:187], v[98:101]
	v_mfma_f32_16x16x32_bf16 v[86:89], v[220:223], v[204:207], v[86:89]
	v_mfma_f32_16x16x32_bf16 v[82:85], v[228:231], v[204:207], v[82:85]
	v_mfma_f32_16x16x32_bf16 v[70:73], v[220:223], v[212:215], v[70:73]
	v_mfma_f32_16x16x32_bf16 v[66:69], v[228:231], v[212:215], v[66:69]
	v_mfma_f32_16x16x32_bf16 v[118:121], v[224:227], v[180:183], v[118:121]
	v_mfma_f32_16x16x32_bf16 v[114:117], v[232:235], v[180:183], v[114:117]
	v_mfma_f32_16x16x32_bf16 v[102:105], v[224:227], v[188:191], v[102:105]
	v_mfma_f32_16x16x32_bf16 v[98:101], v[232:235], v[188:191], v[98:101]
	v_mfma_f32_16x16x32_bf16 v[86:89], v[224:227], v[208:211], v[86:89]
	v_mfma_f32_16x16x32_bf16 v[82:85], v[232:235], v[208:211], v[82:85]
	v_mfma_f32_16x16x32_bf16 v[70:73], v[224:227], v[216:219], v[70:73]
	v_mfma_f32_16x16x32_bf16 v[66:69], v[232:235], v[216:219], v[66:69]
	s_setprio 0
	s_barrier
	s_mov_b32 m0, s74
	v_lshl_add_u64 v[170:171], v[238:239], 0, s[48:49]
	ds_read_b128 v[166:169], v157 offset:49152
	ds_read_b128 v[180:183], v157 offset:50176
	ds_read_b128 v[184:187], v157 offset:51200
	ds_read_b128 v[188:191], v157 offset:52224
	ds_read_b128 v[204:207], v157 offset:53248
	ds_read_b128 v[208:211], v157 offset:54272
	ds_read_b128 v[212:215], v157 offset:55296
	ds_read_b128 v[216:219], v157 offset:56320
	global_load_lds_dwordx4 v[170:171], off
	v_lshl_add_u64 v[170:171], v[240:241], 0, s[48:49]
	s_mov_b32 m0, s75
	s_nop 0
	global_load_lds_dwordx4 v[170:171], off
	s_barrier
; template <class Epi>
; __device__ __forceinline__ void gemm_phase(LAS unsigned char* lds, const GemmD g, const Epi& E) {
;     ...
;         for (int t = 0; t < nt; t += 2) PG8_KITER(t);
;     __device__ __forceinline__ void operator()(const f32x4 (&acc)[2][2][4][2], const Unit& u, int wr, int wc, int fr, int fq) const {
;         const int row0 = u.pm * BM + wr * 64 + fr, col0 = u.pn * BM + wc * 32 + 8 * fq;
; #pragma unroll
;         for (int ai = 0; ai < 2; ++ai)
; #pragma unroll
;             for (int m = 0; m < 4; ++m) { const int row = row0 + ai * HALF + m * 16;
;                 const float* src = row_src(p, row); float* dst = row_dst(p, row); float ss = 0.f;
;                 if (dst) {
; #pragma unroll
;                     for (int bj = 0; bj < 2; ++bj) { const int col = col0 + bj * HALF;
;                         const f32x4 h0 = __builtin_nontemporal_load((const f32x4*)(src + col)), h1 = __builtin_nontemporal_load((const f32x4*)(src + col + 4));
	s_waitcnt lgkmcnt(0)
	s_setprio 1
	s_waitcnt lgkmcnt(0)
	v_mfma_f32_16x16x32_bf16 v[62:65], v[146:149], v[166:169], v[62:65]
	v_mfma_f32_16x16x32_bf16 v[58:61], v[158:161], v[166:169], v[58:61]
	v_mfma_f32_16x16x32_bf16 v[46:49], v[146:149], v[184:187], v[46:49]
	v_mfma_f32_16x16x32_bf16 v[42:45], v[158:161], v[184:187], v[42:45]
	v_mfma_f32_16x16x32_bf16 v[30:33], v[146:149], v[204:207], v[30:33]
	v_mfma_f32_16x16x32_bf16 v[26:29], v[158:161], v[204:207], v[26:29]
	v_mfma_f32_16x16x32_bf16 v[14:17], v[146:149], v[212:215], v[14:17]
	v_mfma_f32_16x16x32_bf16 v[10:13], v[158:161], v[212:215], v[10:13]
	v_mfma_f32_16x16x32_bf16 v[62:65], v[150:153], v[180:183], v[62:65]
	v_mfma_f32_16x16x32_bf16 v[58:61], v[162:165], v[180:183], v[58:61]
	v_mfma_f32_16x16x32_bf16 v[46:49], v[150:153], v[188:191], v[46:49]
	v_mfma_f32_16x16x32_bf16 v[42:45], v[162:165], v[188:191], v[42:45]
	v_mfma_f32_16x16x32_bf16 v[30:33], v[150:153], v[208:211], v[30:33]
	v_mfma_f32_16x16x32_bf16 v[26:29], v[162:165], v[208:211], v[26:29]
	v_mfma_f32_16x16x32_bf16 v[14:17], v[150:153], v[216:219], v[14:17]
	v_mfma_f32_16x16x32_bf16 v[10:13], v[162:165], v[216:219], v[10:13]
	s_setprio 0
	s_barrier
	s_add_u32 s34, s34, 0x80080
	s_addc_u32 s35, s35, 0
	s_add_i32 s56, s56, s97
	v_lshl_add_u64 v[146:147], s[34:35], 0, v[132:133]
	s_mov_b32 m0, s56
	s_nop 0
	global_load_lds_dwordx4 v[146:147], off
	v_lshl_add_u64 v[146:147], s[34:35], 0, v[136:137]
	s_add_i32 m0, s56, 0x2000
	s_nop 0
	global_load_lds_dwordx4 v[146:147], off
	s_add_i32 s95, s95, 2
	s_add_u32 vcc_lo, vcc_lo, 0x100
	s_addc_u32 vcc_hi, vcc_hi, 0
	s_add_u32 s51, s51, 0x100
	s_addc_u32 s66, s66, 0
	s_cmp_gt_u32 s95, 29
	s_waitcnt vmcnt(6)
	s_barrier
	s_setprio 1
	v_mfma_f32_16x16x32_bf16 v[54:57], v[220:223], v[166:169], v[54:57]
	v_mfma_f32_16x16x32_bf16 v[50:53], v[228:231], v[166:169], v[50:53]
	v_mfma_f32_16x16x32_bf16 v[38:41], v[220:223], v[184:187], v[38:41]
	v_mfma_f32_16x16x32_bf16 v[34:37], v[228:231], v[184:187], v[34:37]
	v_mfma_f32_16x16x32_bf16 v[22:25], v[220:223], v[204:207], v[22:25]
	v_mfma_f32_16x16x32_bf16 v[18:21], v[228:231], v[204:207], v[18:21]
	v_mfma_f32_16x16x32_bf16 v[6:9], v[220:223], v[212:215], v[6:9]
	v_mfma_f32_16x16x32_bf16 v[2:5], v[228:231], v[212:215], v[2:5]
	v_mfma_f32_16x16x32_bf16 v[54:57], v[224:227], v[180:183], v[54:57]
	v_mfma_f32_16x16x32_bf16 v[50:53], v[232:235], v[180:183], v[50:53]
	v_mfma_f32_16x16x32_bf16 v[38:41], v[224:227], v[188:191], v[38:41]
	v_mfma_f32_16x16x32_bf16 v[34:37], v[232:235], v[188:191], v[34:37]
	v_mfma_f32_16x16x32_bf16 v[22:25], v[224:227], v[208:211], v[22:25]
	v_mfma_f32_16x16x32_bf16 v[18:21], v[232:235], v[208:211], v[18:21]
	v_mfma_f32_16x16x32_bf16 v[6:9], v[224:227], v[216:219], v[6:9]
	v_mfma_f32_16x16x32_bf16 v[2:5], v[232:235], v[216:219], v[2:5]
	s_setprio 0
	s_barrier
	s_cbranch_scc0 .LBB0_697
	v_lshl_add_u32 v148, s0, 8, v154
	v_readlane_b32 s4, v244, 12
	v_readlane_b32 s5, v244, 13
	v_readlane_b32 s6, v244, 14
	v_readlane_b32 s7, v244, 15
	v_readlane_b32 s12, v244, 22
	v_readlane_b32 s13, v244, 23
	v_lshl_or_b32 v190, s50, 8, v156
	v_mov_b32_e32 v191, 0
	v_mov_b32_e32 v188, 0x1000
	v_lshlrev_b32_e32 v190, 2, v190
	s_mov_b32 s8, 0xfff00000
	s_mov_b32 s9, -1
	s_mov_b32 s10, 0xfbc00000
	s_mov_b32 s11, -1
	v_lshl_add_u64 v[182:183], v[190:191], 0, s[4:5]
	v_lshl_add_u64 v[184:185], v[190:191], 0, s[6:7]
	v_lshl_add_u64 v[186:187], v[190:191], 0, s[12:13]
	v_lshl_add_u64 v[182:183], v[182:183], 0, s[8:9]
	v_lshl_add_u64 v[184:185], v[184:185], 0, s[10:11]
	v_mov_b32_e32 v238, v148
	v_mul_hi_i32 v239, v238, s90
	v_lshlrev_b32_e32 v241, 13, v238
	v_ashrrev_i32_e32 v239, 10, v239
	v_mul_i32_i24_e32 v240, 0xfffff780, v239
	v_lshlrev_b32_e32 v239, 24, v239
	v_add_u32_e32 v240, v240, v238
	v_cmp_gt_i32_e32 vcc, 0x2200, v238
	v_max_i32_e32 v238, 0x80, v240
	v_lshl_add_u32 v239, v238, 13, v239
	v_cndmask_b32_e32 v190, v241, v239, vcc
	v_cndmask_b32_e32 v236, v184, v182, vcc
	v_cndmask_b32_e32 v237, v185, v183, vcc
	v_cndmask_b32_e32 v240, v188, v240, vcc
	v_lshl_add_u64 v[236:237], v[190:191], 0, v[236:237]
	v_add_u32_e32 v190, 0xffffff90, v240
	v_cmp_gt_i32_e32 vcc, 0x80, v240
	v_max_i32_e32 v190, 0, v190
	v_lshlrev_b32_e32 v190, 13, v190
	v_lshl_add_u64 v[238:239], v[190:191], 0, v[186:187]
	v_cndmask_b32_e32 v236, v236, v238, vcc
	v_cndmask_b32_e32 v237, v237, v239, vcc
	global_load_dwordx4 v[204:207], v[236:237], off offset:16 nt
	global_load_dwordx4 v[208:211], v[236:237], off nt
	global_load_dwordx4 v[212:215], v[236:237], off offset:528 nt
	global_load_dwordx4 v[216:219], v[236:237], off offset:512 nt
	v_add_u32_e32 v238, 0x10, v148
	v_mul_hi_i32 v239, v238, s90
	v_lshlrev_b32_e32 v241, 13, v238
	v_ashrrev_i32_e32 v239, 10, v239
	v_mul_i32_i24_e32 v240, 0xfffff780, v239
	v_lshlrev_b32_e32 v239, 24, v239
	v_add_u32_e32 v240, v240, v238
	v_cmp_gt_i32_e32 vcc, 0x2200, v238
	v_max_i32_e32 v238, 0x80, v240
	v_lshl_add_u32 v239, v238, 13, v239
	v_cndmask_b32_e32 v190, v241, v239, vcc
	v_cndmask_b32_e32 v236, v184, v182, vcc
	v_cndmask_b32_e32 v237, v185, v183, vcc
	v_cndmask_b32_e32 v240, v188, v240, vcc
	v_lshl_add_u64 v[236:237], v[190:191], 0, v[236:237]
	v_add_u32_e32 v190, 0xffffff90, v240
	v_cmp_gt_i32_e32 vcc, 0x80, v240
	v_max_i32_e32 v190, 0, v190
	v_lshlrev_b32_e32 v190, 13, v190
	v_lshl_add_u64 v[238:239], v[190:191], 0, v[186:187]
	v_cndmask_b32_e32 v236, v236, v238, vcc
	v_cndmask_b32_e32 v237, v237, v239, vcc
	global_load_dwordx4 v[220:223], v[236:237], off offset:16 nt
	global_load_dwordx4 v[224:227], v[236:237], off nt
	global_load_dwordx4 v[228:231], v[236:237], off offset:528 nt
	global_load_dwordx4 v[232:235], v[236:237], off offset:512 nt
	s_movk_i32 s0, 0x21ff
	v_cmp_lt_i32_e32 vcc, s0, v148
	v_add_u32_e32 v146, 0xffffde00, v148
	s_and_saveexec_b64 s[0:1], vcc
	s_xor_b64 s[0:1], exec, s[0:1]
	s_cbranch_execz .LBB0_700
	v_mov_b32_e32 v147, v1
	v_readlane_b32 s4, v244, 12
	v_lshlrev_b64 v[150:151], 13, v[146:147]
	v_readlane_b32 s6, v244, 14
	v_readlane_b32 s7, v244, 15
	v_readlane_b32 s5, v244, 13
	v_readlane_b32 s8, v244, 16
	v_readlane_b32 s9, v244, 17
	v_readlane_b32 s10, v244, 18
	v_readlane_b32 s11, v244, 19
	v_readlane_b32 s12, v244, 20
	v_readlane_b32 s13, v244, 21
	v_readlane_b32 s14, v244, 22
	v_readlane_b32 s15, v244, 23
	v_readlane_b32 s16, v244, 24
	v_readlane_b32 s17, v244, 25
	v_readlane_b32 s18, v244, 26
	v_readlane_b32 s19, v244, 27
	v_lshl_add_u64 v[150:151], s[6:7], 0, v[150:151]

; template <class Epi>
; __device__ __forceinline__ void gemm_phase(LAS unsigned char* lds, const GemmD g, const Epi& E) {
;     ...
;         for (int t = 0; t < nt; t += 2) PG8_KITER(t);
.LBB0_848:
	s_add_u32 s24, s36, 0xfff00080
	s_addc_u32 s25, s37, -1
	s_add_i32 s75, 0, 0x10000
	v_add_u32_e32 v152, s75, v159
	ds_read_b128 v[140:143], v152
	ds_read_b128 v[144:147], v152 offset:1024
	ds_read_b128 v[148:151], v152 offset:2048
	ds_read_b128 v[152:155], v152 offset:3072
	s_cmp_eq_u32 s74, 28
	s_cselect_b32 s39, s29, s25
	s_cselect_b32 s38, s70, s24
	s_cselect_b32 s25, s27, s73
	s_cselect_b32 s24, s71, s72
	v_lshl_add_u64 v[156:157], s[36:37], 0, v[136:137]
	s_add_i32 m0, s40, 0xc000
	ds_read_b128 v[162:165], v161
	ds_read_b128 v[166:169], v161 offset:1024
	ds_read_b128 v[180:183], v161 offset:2048
	ds_read_b128 v[184:187], v161 offset:3072
	ds_read_b128 v[188:191], v161 offset:4096
	ds_read_b128 v[204:207], v161 offset:5120
	ds_read_b128 v[208:211], v161 offset:6144
	ds_read_b128 v[212:215], v161 offset:7168
	global_load_lds_dwordx4 v[156:157], off
	v_lshl_add_u64 v[156:157], s[36:37], 0, v[138:139]
	s_add_i32 m0, s40, 0xe000
	s_nop 0
	global_load_lds_dwordx4 v[156:157], off
	s_waitcnt lgkmcnt(8)
	s_barrier
	s_waitcnt lgkmcnt(0)
	s_setprio 1
	s_waitcnt lgkmcnt(0)
	v_mfma_f32_16x16x32_bf16 v[126:129], v[140:143], v[162:165], v[126:129]
	v_mfma_f32_16x16x32_bf16 v[122:125], v[148:151], v[162:165], v[122:125]
	v_mfma_f32_16x16x32_bf16 v[110:113], v[140:143], v[180:183], v[110:113]
	v_mfma_f32_16x16x32_bf16 v[106:109], v[148:151], v[180:183], v[106:109]
	v_mfma_f32_16x16x32_bf16 v[94:97], v[140:143], v[188:191], v[94:97]
	v_mfma_f32_16x16x32_bf16 v[90:93], v[148:151], v[188:191], v[90:93]
	v_mfma_f32_16x16x32_bf16 v[78:81], v[140:143], v[208:211], v[78:81]
	v_mfma_f32_16x16x32_bf16 v[74:77], v[148:151], v[208:211], v[74:77]
	v_mfma_f32_16x16x32_bf16 v[126:129], v[144:147], v[166:169], v[126:129]
	v_mfma_f32_16x16x32_bf16 v[122:125], v[152:155], v[166:169], v[122:125]
	v_mfma_f32_16x16x32_bf16 v[110:113], v[144:147], v[184:187], v[110:113]
	v_mfma_f32_16x16x32_bf16 v[106:109], v[152:155], v[184:187], v[106:109]
	v_mfma_f32_16x16x32_bf16 v[94:97], v[144:147], v[204:207], v[94:97]
	v_mfma_f32_16x16x32_bf16 v[90:93], v[152:155], v[204:207], v[90:93]
	v_mfma_f32_16x16x32_bf16 v[78:81], v[144:147], v[212:215], v[78:81]
	v_mfma_f32_16x16x32_bf16 v[74:77], v[152:155], v[212:215], v[74:77]
	s_setprio 0
	s_barrier
	s_add_i32 s83, 0, 0x14000
	v_add_u32_e32 v156, s83, v159
	s_add_i32 s75, s75, s3
	ds_read_b128 v[216:219], v156
	ds_read_b128 v[220:223], v156 offset:1024
	ds_read_b128 v[224:227], v156 offset:2048
	ds_read_b128 v[228:231], v156 offset:3072
	v_lshl_add_u64 v[156:157], s[24:25], 0, v[0:1]
	s_mov_b32 m0, s75
	v_lshl_add_u64 v[170:171], s[24:25], 0, v[134:135]
	global_load_lds_dwordx4 v[156:157], off
	s_add_i32 m0, s75, 0x2000
	s_nop 0
	global_load_lds_dwordx4 v[170:171], off
	s_barrier
	s_waitcnt lgkmcnt(0)
	s_setprio 1
	s_waitcnt lgkmcnt(0)
	v_mfma_f32_16x16x32_bf16 v[118:121], v[216:219], v[162:165], v[118:121]
	v_mfma_f32_16x16x32_bf16 v[114:117], v[224:227], v[162:165], v[114:117]
	v_mfma_f32_16x16x32_bf16 v[102:105], v[216:219], v[180:183], v[102:105]
	v_mfma_f32_16x16x32_bf16 v[98:101], v[224:227], v[180:183], v[98:101]
	v_mfma_f32_16x16x32_bf16 v[86:89], v[216:219], v[188:191], v[86:89]
	v_mfma_f32_16x16x32_bf16 v[82:85], v[224:227], v[188:191], v[82:85]
	v_mfma_f32_16x16x32_bf16 v[70:73], v[216:219], v[208:211], v[70:73]
	v_mfma_f32_16x16x32_bf16 v[66:69], v[224:227], v[208:211], v[66:69]
	v_mfma_f32_16x16x32_bf16 v[118:121], v[220:223], v[166:169], v[118:121]
	v_mfma_f32_16x16x32_bf16 v[114:117], v[228:231], v[166:169], v[114:117]
	v_mfma_f32_16x16x32_bf16 v[102:105], v[220:223], v[184:187], v[102:105]
	v_mfma_f32_16x16x32_bf16 v[98:101], v[228:231], v[184:187], v[98:101]
	v_mfma_f32_16x16x32_bf16 v[86:89], v[220:223], v[204:207], v[86:89]
	v_mfma_f32_16x16x32_bf16 v[82:85], v[228:231], v[204:207], v[82:85]
	v_mfma_f32_16x16x32_bf16 v[70:73], v[220:223], v[212:215], v[70:73]
	v_mfma_f32_16x16x32_bf16 v[66:69], v[228:231], v[212:215], v[66:69]
	s_setprio 0
	s_barrier
	s_mov_b32 m0, s40
	v_lshl_add_u64 v[232:233], s[38:39], 0, v[130:131]
	ds_read_b128 v[162:165], v161 offset:16384
	ds_read_b128 v[166:169], v161 offset:17408
	ds_read_b128 v[180:183], v161 offset:18432
	ds_read_b128 v[184:187], v161 offset:19456
	ds_read_b128 v[188:191], v161 offset:20480
	ds_read_b128 v[204:207], v161 offset:21504
	ds_read_b128 v[208:211], v161 offset:22528
	ds_read_b128 v[212:215], v161 offset:23552
	global_load_lds_dwordx4 v[232:233], off
	v_lshl_add_u64 v[234:235], s[38:39], 0, v[132:133]
	s_mov_b32 m0, s41
	s_nop 0
	global_load_lds_dwordx4 v[234:235], off
	s_barrier
	s_waitcnt lgkmcnt(0)
	s_setprio 1
	s_waitcnt lgkmcnt(0)
	v_mfma_f32_16x16x32_bf16 v[62:65], v[140:143], v[162:165], v[62:65]
	v_mfma_f32_16x16x32_bf16 v[58:61], v[148:151], v[162:165], v[58:61]
	v_mfma_f32_16x16x32_bf16 v[46:49], v[140:143], v[180:183], v[46:49]
	v_mfma_f32_16x16x32_bf16 v[42:45], v[148:151], v[180:183], v[42:45]
	v_mfma_f32_16x16x32_bf16 v[30:33], v[140:143], v[188:191], v[30:33]
	v_mfma_f32_16x16x32_bf16 v[26:29], v[148:151], v[188:191], v[26:29]
	v_mfma_f32_16x16x32_bf16 v[14:17], v[140:143], v[208:211], v[14:17]
	v_mfma_f32_16x16x32_bf16 v[10:13], v[148:151], v[208:211], v[10:13]
	v_mfma_f32_16x16x32_bf16 v[62:65], v[144:147], v[166:169], v[62:65]
	v_mfma_f32_16x16x32_bf16 v[58:61], v[152:155], v[166:169], v[58:61]
	v_mfma_f32_16x16x32_bf16 v[46:49], v[144:147], v[184:187], v[46:49]
	v_mfma_f32_16x16x32_bf16 v[42:45], v[152:155], v[184:187], v[42:45]
	v_mfma_f32_16x16x32_bf16 v[30:33], v[144:147], v[204:207], v[30:33]
	v_mfma_f32_16x16x32_bf16 v[26:29], v[152:155], v[204:207], v[26:29]
	v_mfma_f32_16x16x32_bf16 v[14:17], v[144:147], v[212:215], v[14:17]
	v_mfma_f32_16x16x32_bf16 v[10:13], v[152:155], v[212:215], v[10:13]
	s_setprio 0
	s_barrier
; template <class Epi>
; __device__ __forceinline__ void gemm_phase(LAS unsigned char* lds, const GemmD g, const Epi& E) {
;     ...
;         for (int t = 0; t < nt; t += 2) PG8_KITER(t);
	s_add_u32 s94, s24, 0x100000
	s_addc_u32 s95, s25, 0
	s_add_i32 s75, s83, s3
	v_lshl_add_u64 v[140:141], s[94:95], 0, v[0:1]
	s_mov_b32 m0, s75
	s_nop 0
	global_load_lds_dwordx4 v[140:141], off
	v_lshl_add_u64 v[140:141], s[94:95], 0, v[134:135]
	s_add_i32 m0, s75, 0x2000
	s_nop 0
	global_load_lds_dwordx4 v[140:141], off
	s_waitcnt vmcnt(6)
	s_barrier
	s_setprio 1
	v_mfma_f32_16x16x32_bf16 v[54:57], v[216:219], v[162:165], v[54:57]
	v_mfma_f32_16x16x32_bf16 v[50:53], v[224:227], v[162:165], v[50:53]
	v_mfma_f32_16x16x32_bf16 v[38:41], v[216:219], v[180:183], v[38:41]
	v_mfma_f32_16x16x32_bf16 v[34:37], v[224:227], v[180:183], v[34:37]
	v_mfma_f32_16x16x32_bf16 v[22:25], v[216:219], v[188:191], v[22:25]
	v_mfma_f32_16x16x32_bf16 v[18:21], v[224:227], v[188:191], v[18:21]
	v_mfma_f32_16x16x32_bf16 v[6:9], v[216:219], v[208:211], v[6:9]
	v_mfma_f32_16x16x32_bf16 v[2:5], v[224:227], v[208:211], v[2:5]
	v_mfma_f32_16x16x32_bf16 v[54:57], v[220:223], v[166:169], v[54:57]
	v_mfma_f32_16x16x32_bf16 v[50:53], v[228:231], v[166:169], v[50:53]
	v_mfma_f32_16x16x32_bf16 v[38:41], v[220:223], v[184:187], v[38:41]
	v_mfma_f32_16x16x32_bf16 v[34:37], v[228:231], v[184:187], v[34:37]
	v_mfma_f32_16x16x32_bf16 v[22:25], v[220:223], v[204:207], v[22:25]
	v_mfma_f32_16x16x32_bf16 v[18:21], v[228:231], v[204:207], v[18:21]
	v_mfma_f32_16x16x32_bf16 v[6:9], v[220:223], v[212:215], v[6:9]
	v_mfma_f32_16x16x32_bf16 v[2:5], v[228:231], v[212:215], v[2:5]
	s_setprio 0
	s_barrier
	s_add_i32 s75, 0, 0x18000
	v_add_u32_e32 v152, s75, v159
	ds_read_b128 v[140:143], v152
	ds_read_b128 v[144:147], v152 offset:1024
	ds_read_b128 v[148:151], v152 offset:2048
	ds_read_b128 v[152:155], v152 offset:3072
	s_add_u32 s38, s38, 0x100000
	s_addc_u32 s39, s39, 0
	s_mov_b32 m0, s46
	v_lshl_add_u64 v[216:217], s[38:39], 0, v[130:131]
	ds_read_b128 v[162:165], v161 offset:32768
	ds_read_b128 v[166:169], v161 offset:33792
	ds_read_b128 v[180:183], v161 offset:34816
	ds_read_b128 v[184:187], v161 offset:35840
	ds_read_b128 v[188:191], v161 offset:36864
	ds_read_b128 v[204:207], v161 offset:37888
	ds_read_b128 v[208:211], v161 offset:38912
	ds_read_b128 v[212:215], v161 offset:39936
	global_load_lds_dwordx4 v[216:217], off
	v_lshl_add_u64 v[216:217], s[38:39], 0, v[132:133]
	s_mov_b32 m0, s47
	s_nop 0
	global_load_lds_dwordx4 v[216:217], off
	s_waitcnt lgkmcnt(8)
	s_barrier
	s_waitcnt lgkmcnt(0)
	s_setprio 1
	s_waitcnt lgkmcnt(0)
	v_mfma_f32_16x16x32_bf16 v[126:129], v[140:143], v[162:165], v[126:129]
	v_mfma_f32_16x16x32_bf16 v[122:125], v[148:151], v[162:165], v[122:125]
	v_mfma_f32_16x16x32_bf16 v[110:113], v[140:143], v[180:183], v[110:113]
	v_mfma_f32_16x16x32_bf16 v[106:109], v[148:151], v[180:183], v[106:109]
	v_mfma_f32_16x16x32_bf16 v[94:97], v[140:143], v[188:191], v[94:97]
	v_mfma_f32_16x16x32_bf16 v[90:93], v[148:151], v[188:191], v[90:93]
	v_mfma_f32_16x16x32_bf16 v[78:81], v[140:143], v[208:211], v[78:81]
	v_mfma_f32_16x16x32_bf16 v[74:77], v[148:151], v[208:211], v[74:77]
	v_mfma_f32_16x16x32_bf16 v[126:129], v[144:147], v[166:169], v[126:129]
	v_mfma_f32_16x16x32_bf16 v[122:125], v[152:155], v[166:169], v[122:125]
	v_mfma_f32_16x16x32_bf16 v[110:113], v[144:147], v[184:187], v[110:113]
	v_mfma_f32_16x16x32_bf16 v[106:109], v[152:155], v[184:187], v[106:109]
	v_mfma_f32_16x16x32_bf16 v[94:97], v[144:147], v[204:207], v[94:97]
	v_mfma_f32_16x16x32_bf16 v[90:93], v[152:155], v[204:207], v[90:93]
	v_mfma_f32_16x16x32_bf16 v[78:81], v[144:147], v[212:215], v[78:81]
	v_mfma_f32_16x16x32_bf16 v[74:77], v[152:155], v[212:215], v[74:77]
	s_setprio 0
	s_barrier
	s_add_i32 s38, 0, 0x1c000
	s_add_i32 s39, s75, s3
	v_add_u32_e32 v203, s38, v159
	v_lshl_add_u64 v[156:157], v[156:157], 0, s[48:49]
	s_mov_b32 m0, s39
	ds_read_b128 v[216:219], v203
	ds_read_b128 v[220:223], v203 offset:1024
	ds_read_b128 v[224:227], v203 offset:2048
	ds_read_b128 v[228:231], v203 offset:3072
	global_load_lds_dwordx4 v[156:157], off
	v_lshl_add_u64 v[156:157], v[170:171], 0, s[48:49]
	s_add_i32 m0, s39, 0x2000
	s_nop 0
	global_load_lds_dwordx4 v[156:157], off
	s_barrier
	s_waitcnt lgkmcnt(0)
	s_setprio 1
	s_waitcnt lgkmcnt(0)
	v_mfma_f32_16x16x32_bf16 v[118:121], v[216:219], v[162:165], v[118:121]
	v_mfma_f32_16x16x32_bf16 v[114:117], v[224:227], v[162:165], v[114:117]
	v_mfma_f32_16x16x32_bf16 v[102:105], v[216:219], v[180:183], v[102:105]
	v_mfma_f32_16x16x32_bf16 v[98:101], v[224:227], v[180:183], v[98:101]
	v_mfma_f32_16x16x32_bf16 v[86:89], v[216:219], v[188:191], v[86:89]
	v_mfma_f32_16x16x32_bf16 v[82:85], v[224:227], v[188:191], v[82:85]
	v_mfma_f32_16x16x32_bf16 v[70:73], v[216:219], v[208:211], v[70:73]
	v_mfma_f32_16x16x32_bf16 v[66:69], v[224:227], v[208:211], v[66:69]
	v_mfma_f32_16x16x32_bf16 v[118:121], v[220:223], v[166:169], v[118:121]
	v_mfma_f32_16x16x32_bf16 v[114:117], v[228:231], v[166:169], v[114:117]
	v_mfma_f32_16x16x32_bf16 v[102:105], v[220:223], v[184:187], v[102:105]
	v_mfma_f32_16x16x32_bf16 v[98:101], v[228:231], v[184:187], v[98:101]
	v_mfma_f32_16x16x32_bf16 v[86:89], v[220:223], v[204:207], v[86:89]
	v_mfma_f32_16x16x32_bf16 v[82:85], v[228:231], v[204:207], v[82:85]
	v_mfma_f32_16x16x32_bf16 v[70:73], v[220:223], v[212:215], v[70:73]
	v_mfma_f32_16x16x32_bf16 v[66:69], v[228:231], v[212:215], v[66:69]
	s_setprio 0
	s_barrier
	s_mov_b32 m0, s50
	v_lshl_add_u64 v[156:157], v[232:233], 0, s[48:49]
	ds_read_b128 v[162:165], v161 offset:49152
	ds_read_b128 v[166:169], v161 offset:50176
	ds_read_b128 v[180:183], v161 offset:51200
	ds_read_b128 v[184:187], v161 offset:52224
	ds_read_b128 v[188:191], v161 offset:53248
	ds_read_b128 v[204:207], v161 offset:54272
	ds_read_b128 v[208:211], v161 offset:55296
	ds_read_b128 v[212:215], v161 offset:56320
	global_load_lds_dwordx4 v[156:157], off
	v_lshl_add_u64 v[156:157], v[234:235], 0, s[48:49]
	s_mov_b32 m0, s51
	s_nop 0
	global_load_lds_dwordx4 v[156:157], off
	s_barrier
; __device__ __forceinline__ float bflo(unsigned w) { return __uint_as_float(w << 16); }
; __device__ __forceinline__ float bfhi(unsigned w) { return __uint_as_float(w & 0xffff0000u); }
; template <class Epi>
; __device__ __forceinline__ void gemm_phase(LAS unsigned char* lds, const GemmD g, const Epi& E) {
;     ...
;         for (int t = 0; t < nt; t += 2) PG8_KITER(t);
;     __device__ __forceinline__ void operator()(const f32x4 (&acc)[2][2][4][2], const Unit& u, int wr, int wc, int fr, int fq) const {
;         const int row0 = u.pm * BM + wr * 64 + fr, col0 = u.pn * BM + wc * 32 + 8 * fq;
; #pragma unroll
;         for (int ai = 0; ai < 2; ++ai)
; #pragma unroll
;             for (int m = 0; m < 4; ++m) { const int row = row0 + ai * HALF + m * 16;
; #pragma unroll
;                 for (int bj = 0; bj < 2; ++bj) { const int col = col0 + bj * HALF;
;                     const u32x4 gp = *(const u32x4*)(proj + (size_t)row * NPROJ + C_GP + col);
;                     f32x4 f0 = (f32x4){bflo(gp.x), bfhi(gp.x), bflo(gp.y), bfhi(gp.y)}, f1 = (f32x4){bflo(gp.z), bfhi(gp.z), bflo(gp.w), bfhi(gp.w)};
;                     if (which == 0) { const u32x4 r = *(const u32x4*)(proj + (size_t)row * NPROJ + C_GS + col);
;                         f0 *= (f32x4){bflo(r.x), bfhi(r.x), bflo(r.y), bfhi(r.y)}; f1 *= (f32x4){bflo(r.z), bfhi(r.z), bflo(r.w), bfhi(r.w)}; }
;                     float* d = F + (size_t)(row - 8192) * DM + col;
;                     *(f32x4*)d = acc[ai][bj][m][0] * f0; *(f32x4*)(d + 4) = acc[ai][bj][m][1] * f1; } }
	s_waitcnt lgkmcnt(0)
	s_setprio 1
	s_waitcnt lgkmcnt(0)
	v_mfma_f32_16x16x32_bf16 v[62:65], v[140:143], v[162:165], v[62:65]
	v_mfma_f32_16x16x32_bf16 v[58:61], v[148:151], v[162:165], v[58:61]
	v_mfma_f32_16x16x32_bf16 v[46:49], v[140:143], v[180:183], v[46:49]
	v_mfma_f32_16x16x32_bf16 v[42:45], v[148:151], v[180:183], v[42:45]
	v_mfma_f32_16x16x32_bf16 v[30:33], v[140:143], v[188:191], v[30:33]
	v_mfma_f32_16x16x32_bf16 v[26:29], v[148:151], v[188:191], v[26:29]
	v_mfma_f32_16x16x32_bf16 v[14:17], v[140:143], v[208:211], v[14:17]
	v_mfma_f32_16x16x32_bf16 v[10:13], v[148:151], v[208:211], v[10:13]
	v_mfma_f32_16x16x32_bf16 v[62:65], v[144:147], v[166:169], v[62:65]
	v_mfma_f32_16x16x32_bf16 v[58:61], v[152:155], v[166:169], v[58:61]
	v_mfma_f32_16x16x32_bf16 v[46:49], v[144:147], v[184:187], v[46:49]
	v_mfma_f32_16x16x32_bf16 v[42:45], v[152:155], v[184:187], v[42:45]
	v_mfma_f32_16x16x32_bf16 v[30:33], v[144:147], v[204:207], v[30:33]
	v_mfma_f32_16x16x32_bf16 v[26:29], v[152:155], v[204:207], v[26:29]
	v_mfma_f32_16x16x32_bf16 v[14:17], v[144:147], v[212:215], v[14:17]
	v_mfma_f32_16x16x32_bf16 v[10:13], v[152:155], v[212:215], v[10:13]
	s_setprio 0
	s_barrier
	s_add_u32 s24, s24, 0x100080
	s_addc_u32 s25, s25, 0
	s_add_i32 s38, s38, s3
	v_lshl_add_u64 v[140:141], s[24:25], 0, v[0:1]
	s_mov_b32 m0, s38
	s_nop 0
	global_load_lds_dwordx4 v[140:141], off
	v_lshl_add_u64 v[140:141], s[24:25], 0, v[134:135]
	s_add_i32 m0, s38, 0x2000
	s_nop 0
	global_load_lds_dwordx4 v[140:141], off
	s_add_i32 s74, s74, 2
	s_add_u32 s36, s36, 0x100
	s_addc_u32 s37, s37, 0
	s_add_u32 s72, s72, 0x100
	s_addc_u32 s73, s73, 0
	s_cmp_gt_u32 s74, 29
	s_waitcnt vmcnt(6)
	s_barrier
	s_setprio 1
	v_mfma_f32_16x16x32_bf16 v[54:57], v[216:219], v[162:165], v[54:57]
	v_mfma_f32_16x16x32_bf16 v[50:53], v[224:227], v[162:165], v[50:53]
	v_mfma_f32_16x16x32_bf16 v[38:41], v[216:219], v[180:183], v[38:41]
	v_mfma_f32_16x16x32_bf16 v[34:37], v[224:227], v[180:183], v[34:37]
	v_mfma_f32_16x16x32_bf16 v[22:25], v[216:219], v[188:191], v[22:25]
	v_mfma_f32_16x16x32_bf16 v[18:21], v[224:227], v[188:191], v[18:21]
	v_mfma_f32_16x16x32_bf16 v[6:9], v[216:219], v[208:211], v[6:9]
	v_mfma_f32_16x16x32_bf16 v[2:5], v[224:227], v[208:211], v[2:5]
	v_mfma_f32_16x16x32_bf16 v[54:57], v[220:223], v[166:169], v[54:57]
	v_mfma_f32_16x16x32_bf16 v[50:53], v[228:231], v[166:169], v[50:53]
	v_mfma_f32_16x16x32_bf16 v[38:41], v[220:223], v[184:187], v[38:41]
	v_mfma_f32_16x16x32_bf16 v[34:37], v[228:231], v[184:187], v[34:37]
	v_mfma_f32_16x16x32_bf16 v[22:25], v[220:223], v[204:207], v[22:25]
	v_mfma_f32_16x16x32_bf16 v[18:21], v[228:231], v[204:207], v[18:21]
	v_mfma_f32_16x16x32_bf16 v[6:9], v[220:223], v[212:215], v[6:9]
	v_mfma_f32_16x16x32_bf16 v[2:5], v[228:231], v[212:215], v[2:5]
	s_setprio 0
	s_barrier
	s_cbranch_scc0 .LBB0_848
	v_lshl_add_u32 v142, s66, 8, v158
	v_mov_b64_e32 v[144:145], s[92:93]
	v_lshl_or_b32 v140, s57, 8, v160
	v_mad_i64_i32 v[144:145], s[24:25], v142, s91, v[144:145]
	v_lshl_add_u64 v[148:149], v[144:145], 0, s[76:77]
	v_ashrrev_i32_e32 v141, 31, v140
	v_lshl_add_u64 v[146:147], v[140:141], 1, v[148:149]
	v_mov_b32_e32 v240, v146
	v_mov_b32_e32 v241, v147
	s_mov_b32 s74, 0x0
	s_mov_b32 s75, 0
	v_lshl_add_u64 v[204:205], v[240:241], 0, s[74:75]
	global_load_dwordx4 v[204:207], v[204:205], off
	s_mov_b32 s74, 0xfffff000
	s_mov_b32 s75, -1
	v_lshl_add_u64 v[208:209], v[240:241], 0, s[74:75]
	global_load_dwordx4 v[208:211], v[208:209], off
	s_mov_b32 s74, 0x100
	s_mov_b32 s75, 0
	v_lshl_add_u64 v[212:213], v[240:241], 0, s[74:75]
	global_load_dwordx4 v[212:215], v[212:213], off
	s_mov_b32 s74, 0xfffff100
	s_mov_b32 s75, -1
	v_lshl_add_u64 v[216:217], v[240:241], 0, s[74:75]
	global_load_dwordx4 v[216:219], v[216:217], off
	s_mov_b32 s74, 0x6a000
	s_mov_b32 s75, 0
	v_lshl_add_u64 v[220:221], v[240:241], 0, s[74:75]
	global_load_dwordx4 v[220:223], v[220:221], off
	s_mov_b32 s74, 0x69000
	s_mov_b32 s75, 0
	v_lshl_add_u64 v[224:225], v[240:241], 0, s[74:75]
	global_load_dwordx4 v[224:227], v[224:225], off
	s_mov_b32 s74, 0x6a100
	s_mov_b32 s75, 0
	v_lshl_add_u64 v[228:229], v[240:241], 0, s[74:75]
	global_load_dwordx4 v[228:231], v[228:229], off
	s_mov_b32 s74, 0x69100
	s_mov_b32 s75, 0
	v_lshl_add_u64 v[232:233], v[240:241], 0, s[74:75]
	global_load_dwordx4 v[232:235], v[232:233], off
	s_mov_b32 s74, 0xd4000
	s_mov_b32 s75, 0
	v_lshl_add_u64 v[236:237], v[240:241], 0, s[74:75]
	global_load_dwordx4 v[236:239], v[236:237], off
	s_mov_b32 s74, 0xd3000
	s_mov_b32 s75, 0
	v_lshl_add_u64 v[180:181], v[240:241], 0, s[74:75]
	global_load_dwordx4 v[180:183], v[180:181], off
	s_mov_b32 s74, 0xd4100
	s_mov_b32 s75, 0
	v_lshl_add_u64 v[184:185], v[240:241], 0, s[74:75]
	global_load_dwordx4 v[184:187], v[184:185], off
	s_mov_b32 s74, 0xd3100
	s_mov_b32 s75, 0
	v_lshl_add_u64 v[188:189], v[240:241], 0, s[74:75]
	global_load_dwordx4 v[188:191], v[188:189], off
	s_mov_b32 s74, 0x13e000
	s_mov_b32 s75, 0
	v_lshl_add_u64 v[166:167], v[240:241], 0, s[74:75]
	global_load_dwordx4 v[166:169], v[166:167], off
	s_mov_b32 s74, 0x13d000
	s_mov_b32 s75, 0
	v_lshl_add_u64 v[246:247], v[240:241], 0, s[74:75]
	global_load_dwordx4 v[246:249], v[246:247], off
	v_cndmask_b32_e64 v143, 0, 1, s[62:63]
	v_cmp_ne_u32_e64 s[36:37], 1, v143
	s_andn2_b64 vcc, exec, s[62:63]
	s_waitcnt vmcnt(13)
	v_mov_b32_e32 v150, v204
	v_mov_b32_e32 v151, v205
	v_mov_b32_e32 v152, v206
	v_mov_b32_e32 v153, v207
	s_mov_b32 s74, 0x13e100
	s_mov_b32 s75, 0
	v_lshl_add_u64 v[204:205], v[240:241], 0, s[74:75]
	global_load_dwordx4 v[204:207], v[204:205], off
	v_lshlrev_b32_e32 v154, 16, v150
	v_and_b32_e32 v155, 0xffff0000, v150
	v_lshlrev_b32_e32 v156, 16, v151
	v_and_b32_e32 v157, 0xffff0000, v151
	v_lshlrev_b32_e32 v150, 16, v152
	v_and_b32_e32 v151, 0xffff0000, v152
	v_lshlrev_b32_e32 v152, 16, v153
	v_and_b32_e32 v153, 0xffff0000, v153
	s_cbranch_vccnz .LBB0_851
	v_lshl_add_u64 v[146:147], v[140:141], 1, v[144:145]
	v_add_co_u32_e32 v146, vcc, 0x4000, v146
	s_nop 1
	v_addc_co_u32_e32 v147, vcc, 0, v147, vcc
	s_waitcnt vmcnt(13)
	v_mov_b32_e32 v162, v208
	v_mov_b32_e32 v163, v209
	v_mov_b32_e32 v164, v210
	v_mov_b32_e32 v165, v211
	v_lshlrev_b32_e32 v146, 16, v162
	v_and_b32_e32 v147, 0xffff0000, v162
	v_lshlrev_b32_e32 v162, 16, v163
	v_and_b32_e32 v163, 0xffff0000, v163
	v_pk_mul_f32 v[156:157], v[156:157], v[162:163]
	v_pk_mul_f32 v[154:155], v[154:155], v[146:147]
	v_lshlrev_b32_e32 v146, 16, v164
	v_and_b32_e32 v147, 0xffff0000, v164
	v_lshlrev_b32_e32 v162, 16, v165
	v_and_b32_e32 v163, 0xffff0000, v165
	v_pk_mul_f32 v[152:153], v[152:153], v[162:163]
	v_pk_mul_f32 v[150:151], v[150:151], v[146:147]
